# nt (streaming) cache hint on write-once / read-once traffic: ACT stores, final f32 output stores, SWA and GLA-output stores, prologue x loads
# speedup vs baseline: 1.0564x; 1.0151x over previous
.LBB0_63:
	s_waitcnt lgkmcnt(0)
	global_load_dwordx4 v[16:19], v[8:9], off offset:-2048 nt
	global_load_dwordx4 v[20:23], v[8:9], off offset:-1024 nt
	global_load_dwordx4 v[24:27], v[8:9], off nt
	global_load_dwordx4 v[28:31], v[8:9], off offset:1024 nt
	v_lshl_add_u64 v[32:33], s[16:17], 0, v[6:7]
	v_add_co_u32_e64 v32, s[8:9], s3, v32
	s_waitcnt vmcnt(3)
	v_mul_f32_e32 v3, v17, v17
	v_mul_f32_e32 v34, v19, v19
	s_waitcnt vmcnt(2)
	v_mul_f32_e32 v35, v21, v21
	v_mul_f32_e32 v36, v23, v23
	s_waitcnt vmcnt(1)
	v_mul_f32_e32 v37, v25, v25
	v_mul_f32_e32 v38, v27, v27
	v_fmac_f32_e32 v3, v16, v16
	v_fmac_f32_e32 v34, v18, v18
	v_fmac_f32_e32 v35, v20, v20
	v_fmac_f32_e32 v36, v22, v22
	s_waitcnt vmcnt(0)
	v_mul_f32_e32 v39, v29, v29
	v_mul_f32_e32 v40, v31, v31
	v_fmac_f32_e32 v37, v24, v24
	v_fmac_f32_e32 v38, v26, v26
	v_add_f32_e32 v3, v3, v34
	v_add_f32_e32 v34, v35, v36
	v_fmac_f32_e32 v39, v28, v28
	v_fmac_f32_e32 v40, v30, v30
	v_add_f32_e32 v35, v37, v38
	v_add_f32_e32 v3, v3, v34
	v_add_f32_e32 v36, v39, v40
	v_add_f32_e32 v3, v3, v35
	v_add_f32_e32 v3, v3, v36
	ds_bpermute_b32 v34, v1, v3
	v_bfe_u32 v41, v16, 16, 1
	v_bfe_u32 v43, v18, 16, 1
	v_bfe_u32 v47, v22, 16, 1
	v_bfe_u32 v42, v17, 16, 1
	s_waitcnt lgkmcnt(0)
	v_add_f32_e32 v3, v3, v34
	ds_bpermute_b32 v34, v11, v3
	v_bfe_u32 v44, v19, 16, 1
	v_bfe_u32 v48, v23, 16, 1
	v_add3_u32 v16, v16, v41, s1
	v_add3_u32 v18, v18, v43, s1
	s_waitcnt lgkmcnt(0)
	v_add_f32_e32 v3, v3, v34
	ds_bpermute_b32 v34, v12, v3
	v_add3_u32 v22, v22, v47, s1
	v_add3_u32 v17, v17, v42, s1
	v_add3_u32 v19, v19, v44, s1
	v_add3_u32 v23, v23, v48, s1
	s_waitcnt lgkmcnt(0)
	v_add_f32_e32 v3, v3, v34
	ds_bpermute_b32 v34, v13, v3
	v_lshrrev_b32_e32 v16, 16, v16
	v_lshrrev_b32_e32 v18, 16, v18
	v_lshrrev_b32_e32 v22, 16, v22
	v_and_or_b32 v16, v17, s2, v16
	s_waitcnt lgkmcnt(0)
	v_add_f32_e32 v3, v3, v34
	v_and_or_b32 v17, v19, s2, v18
	v_and_or_b32 v19, v23, s2, v22
	ds_bpermute_b32 v23, v14, v3
	v_bfe_u32 v45, v20, 16, 1
	v_bfe_u32 v49, v24, 16, 1
	v_bfe_u32 v51, v26, 16, 1
	v_bfe_u32 v46, v21, 16, 1
	v_bfe_u32 v50, v25, 16, 1
	v_bfe_u32 v52, v27, 16, 1
	v_add3_u32 v20, v20, v45, s1
	v_add3_u32 v24, v24, v49, s1
	v_add3_u32 v26, v26, v51, s1
	v_addc_co_u32_e64 v33, s[8:9], 0, v33, s[8:9]
	v_add3_u32 v21, v21, v46, s1
	v_add3_u32 v25, v25, v50, s1
	v_add3_u32 v27, v27, v52, s1
	v_lshrrev_b32_e32 v20, 16, v20
	v_lshrrev_b32_e32 v24, 16, v24
	v_lshrrev_b32_e32 v26, 16, v26
	s_waitcnt lgkmcnt(0)
	v_add_f32_e32 v3, v3, v23
	v_and_or_b32 v18, v21, s2, v20
	v_and_or_b32 v20, v25, s2, v24
	v_and_or_b32 v21, v27, s2, v26
	global_store_dwordx2 v[32:33], v[16:17], off
	global_store_dwordx2 v[32:33], v[18:19], off offset:512
	global_store_dwordx2 v[32:33], v[20:21], off offset:1024
	ds_bpermute_b32 v16, v15, v3
	v_bfe_u32 v53, v28, 16, 1
	v_bfe_u32 v55, v30, 16, 1
	v_bfe_u32 v54, v29, 16, 1
	v_add3_u32 v28, v28, v53, s1
	v_add3_u32 v30, v30, v55, s1
	v_bfe_u32 v18, v31, 16, 1
	v_add3_u32 v29, v29, v54, s1
	v_lshrrev_b32_e32 v28, 16, v28
	v_lshrrev_b32_e32 v17, 16, v30
	v_add3_u32 v18, v31, v18, s1
	v_and_or_b32 v22, v29, s2, v28
	v_and_or_b32 v23, v18, s2, v17
	global_store_dwordx2 v[32:33], v[22:23], off offset:1536
	s_and_saveexec_b64 s[8:9], vcc
	s_cbranch_execz .LBB0_62
	s_waitcnt lgkmcnt(0)
	v_add_f32_e32 v3, v3, v16
	v_cndmask_b32_e64 v3, 0, v3, s[6:7]
	v_lshl_add_u64 v[16:17], s[16:17], 0, v[4:5]
	global_store_dword v[16:17], v3, off
	s_branch .LBB0_62

.LBB0_428:
	s_waitcnt vmcnt(3)
	v_lshlrev_b32_e32 v186, 16, v104
	v_and_b32_e32 v187, 0xffff0000, v104
	v_lshlrev_b32_e32 v182, 16, v105
	v_and_b32_e32 v183, 0xffff0000, v105
	v_pk_mul_f32 v[104:105], v[186:187], v[186:187]
	v_pk_mul_f32 v[184:185], v[182:183], v[182:183]
	v_add_f32_e32 v1, v104, v105
	v_lshlrev_b32_e32 v180, 16, v106
	v_and_b32_e32 v181, 0xffff0000, v106
	v_add_f32_e32 v1, v184, v1
	v_lshlrev_b32_e32 v176, 16, v107
	v_and_b32_e32 v177, 0xffff0000, v107
	v_pk_mul_f32 v[106:107], v[180:181], v[180:181]
	v_add_f32_e32 v1, v185, v1
	v_add_f32_e32 v1, v106, v1
	v_pk_mul_f32 v[178:179], v[176:177], v[176:177]
	v_add_f32_e32 v1, v107, v1
	s_waitcnt vmcnt(2)
	v_lshlrev_b32_e32 v174, 16, v108
	v_and_b32_e32 v175, 0xffff0000, v108
	v_add_f32_e32 v1, v178, v1
	v_lshlrev_b32_e32 v170, 16, v109
	v_and_b32_e32 v171, 0xffff0000, v109
	v_pk_mul_f32 v[108:109], v[174:175], v[174:175]
	v_add_f32_e32 v1, v179, v1
	v_add_f32_e32 v1, v108, v1
	v_pk_mul_f32 v[172:173], v[170:171], v[170:171]
	v_add_f32_e32 v1, v109, v1
	v_lshlrev_b32_e32 v160, 16, v110
	v_and_b32_e32 v161, 0xffff0000, v110
	v_add_f32_e32 v1, v172, v1
	v_lshlrev_b32_e32 v154, 16, v111
	v_and_b32_e32 v155, 0xffff0000, v111
	v_pk_mul_f32 v[110:111], v[160:161], v[160:161]
	v_add_f32_e32 v1, v173, v1
	v_add_f32_e32 v1, v110, v1
	v_pk_mul_f32 v[158:159], v[154:155], v[154:155]
	v_add_f32_e32 v1, v111, v1
	v_add_f32_e32 v1, v158, v1
	v_add_f32_e32 v1, v159, v1
	ds_bpermute_b32 v104, v141, v1
	v_lshlrev_b32_e32 v3, 2, v3
	v_sub_u32_e32 v3, v0, v3
	s_mov_b32 s17, 0x40400000
	s_mov_b32 s18, 0x41800000
	s_waitcnt lgkmcnt(0)
	v_add_f32_e32 v1, v1, v104
	ds_bpermute_b32 v104, v142, v1
	s_mov_b32 s19, 0x41880000
	s_mov_b32 s20, 0x41900000
	s_mov_b32 s21, 0x41980000
	s_mov_b32 s22, 0x42000000
	s_waitcnt lgkmcnt(0)
	v_add_f32_e32 v1, v1, v104
	v_fmamk_f32 v1, v1, 0x3c800000, v209
	v_cmp_gt_f32_e32 vcc, s68, v1
	v_mul_f32_e32 v104, 0x4b800000, v1
	s_mov_b32 s16, 0x42800000
	v_cndmask_b32_e32 v1, v1, v104, vcc
	v_rsq_f32_e32 v1, v1
	s_movk_i32 s94, 0x210
	v_lshlrev_b64 v[132:133], 11, v[132:133]
	v_lshl_add_u64 v[132:133], s[86:87], 0, v[132:133]
	v_mul_f32_e32 v104, 0x45800000, v1
	v_cndmask_b32_e32 v1, v1, v104, vcc
	v_mul_f32_e32 v158, 0x3e38aa3b, v1
	v_pk_mul_f32 v[104:105], v[158:159], v[186:187] op_sel_hi:[0,1]
	v_pk_mul_f32 v[106:107], v[158:159], v[182:183] op_sel_hi:[0,1]
	v_pk_mul_f32 v[104:105], v[4:5], v[104:105]
	v_pk_mul_f32 v[106:107], v[6:7], v[106:107]
	v_cvt_pk_bf16_f32 v104, v104, v105
	v_cvt_pk_bf16_f32 v105, v106, v107
	v_pk_mul_f32 v[106:107], v[158:159], v[180:181] op_sel_hi:[0,1]
	v_pk_mul_f32 v[108:109], v[158:159], v[176:177] op_sel_hi:[0,1]
	v_pk_mul_f32 v[106:107], v[8:9], v[106:107]
	v_pk_mul_f32 v[108:109], v[10:11], v[108:109]
	v_cvt_pk_bf16_f32 v106, v106, v107
	v_cvt_pk_bf16_f32 v107, v108, v109
	v_pk_mul_f32 v[108:109], v[158:159], v[174:175] op_sel_hi:[0,1]
	v_pk_mul_f32 v[110:111], v[158:159], v[170:171] op_sel_hi:[0,1]
	v_cvt_f32_u32_e32 v1, s9
	v_pk_mul_f32 v[108:109], v[12:13], v[108:109]
	v_pk_mul_f32 v[110:111], v[14:15], v[110:111]
	v_mfma_f32_16x16x32_bf16 v[170:173], v[24:27], v[104:107], 0
	v_cvt_pk_bf16_f32 v108, v108, v109
	v_cvt_pk_bf16_f32 v109, v110, v111
	v_pk_mul_f32 v[110:111], v[158:159], v[160:161] op_sel_hi:[0,1]
	v_mfma_f32_16x16x32_bf16 v[174:177], v[32:35], v[104:107], 0
	v_mul_f32_e64 v154, v158, v154
	v_mul_f32_e64 v155, v158, v155
	v_pk_mul_f32 v[110:111], v[16:17], v[110:111]
	v_pk_mul_f32 v[154:155], v[18:19], v[154:155]
	v_mfma_f32_16x16x32_bf16 v[178:181], v[40:43], v[104:107], 0
	v_cvt_pk_bf16_f32 v110, v110, v111
	v_cvt_pk_bf16_f32 v111, v154, v155
	v_cmp_lt_f32_e32 vcc, s57, v1
	v_mfma_f32_16x16x32_bf16 v[182:185], v[48:51], v[104:107], 0
	s_and_b64 s[40:41], vcc, exec
	s_cselect_b32 s40, 0xffffffc0, 0
	s_cmp_eq_u32 s42, 1
	v_mfma_f32_16x16x32_bf16 v[186:189], v[56:59], v[104:107], 0
	v_lshl_add_u64 v[132:133], v[134:135], 1, v[132:133]
	v_lshl_add_u64 v[128:129], v[128:129], 0, s[76:77]
	v_mfma_f32_16x16x32_bf16 v[190:193], v[64:67], v[104:107], 0
	v_mfma_f32_16x16x32_bf16 v[194:197], v[72:75], v[104:107], 0
	v_mfma_f32_16x16x32_bf16 v[198:201], v[80:83], v[104:107], 0
	v_mfma_f32_16x16x32_bf16 v[104:107], v[88:91], v[104:107], 0
	v_mfma_f32_16x16x32_bf16 v[170:173], v[28:31], v[108:111], v[170:173]
	v_mfma_f32_16x16x32_bf16 v[174:177], v[36:39], v[108:111], v[174:177]
	v_mfma_f32_16x16x32_bf16 v[178:181], v[44:47], v[108:111], v[178:181]
	v_mfma_f32_16x16x32_bf16 v[182:185], v[52:55], v[108:111], v[182:185]
	v_mfma_f32_16x16x32_bf16 v[186:189], v[60:63], v[108:111], v[186:189]
	v_mfma_f32_16x16x32_bf16 v[190:193], v[68:71], v[108:111], v[190:193]
	v_mfma_f32_16x16x32_bf16 v[194:197], v[76:79], v[108:111], v[194:197]
	v_mfma_f32_16x16x32_bf16 v[198:201], v[84:87], v[108:111], v[198:201]
	v_mfma_f32_16x16x32_bf16 v[104:107], v[92:95], v[108:111], v[104:107]
	v_cndmask_b32_e32 v108, 0, v215, vcc
	v_sub_f32_e32 v1, v108, v1
	v_exp_f32_e32 v1, v1
	s_cselect_b64 vcc, -1, 0
	v_add_u32_e32 v110, 0x80, v3
	v_cvt_f32_i32_e32 v157, v110
	v_ldexp_f32 v109, v1, s40
	v_cndmask_b32_e32 v1, v23, v21, vcc
	v_cmp_gt_i32_e32 vcc, 0, v3
	s_and_b64 s[46:47], s[78:79], vcc
	v_cmp_gt_i32_e32 vcc, 1, v3
	s_and_b64 s[48:49], s[78:79], vcc
	v_cmp_gt_i32_e32 vcc, 2, v3
	s_and_b64 s[50:51], s[78:79], vcc
	v_cmp_gt_i32_e32 vcc, 3, v3
	s_and_b64 s[52:53], s[78:79], vcc
	v_cmp_lt_i32_e32 vcc, -1, v3
	v_mul_f32_e32 v108, 0x3fb8aa3b, v109
	s_and_b64 s[44:45], s[84:85], vcc
	v_cmp_lt_i32_e32 vcc, 0, v3
	s_and_b64 s[42:43], s[84:85], vcc
	v_cmp_lt_i32_e32 vcc, 1, v3
	v_pk_mul_f32 v[110:111], v[108:109], v[156:157] op_sel_hi:[0,1]
	s_and_b64 s[40:41], s[84:85], vcc
	v_cmp_lt_i32_e32 vcc, 2, v3
	v_fma_f32 v3, v108, 0, -v111
	v_fma_f32 v109, v109, s65, -v111
	v_add_f32_e32 v3, v3, v170
	v_add_f32_e32 v109, v109, v171
	v_fma_f32 v123, v108, 2.0, -v111
	v_fma_f32 v125, v108, s17, -v111
	v_mul_f32_e32 v121, 0x3fb8aa3b, v1
	v_cndmask_b32_e64 v3, v216, v3, s[46:47]
	v_cndmask_b32_e64 v109, v216, v109, s[48:49]
	v_add_f32_e32 v123, v123, v172
	v_add_f32_e32 v125, v125, v173
	v_fma_f32 v154, v108, s18, -v111
	v_fma_f32 v155, v108, s19, -v111
	v_max3_f32 v121, v121, v3, v109
	v_cndmask_b32_e64 v123, v216, v123, s[50:51]
	v_cndmask_b32_e64 v125, v216, v125, s[52:53]
	v_add_f32_e32 v154, v154, v174
	v_add_f32_e32 v155, v155, v175
	v_fma_f32 v157, v108, s20, -v111
	v_fma_f32 v158, v108, s21, -v111
	v_max3_f32 v121, v121, v123, v125
	v_cndmask_b32_e64 v154, v216, v154, s[24:25]
	v_cndmask_b32_e64 v155, v216, v155, s[24:25]
	v_add_f32_e32 v157, v157, v176
	v_add_f32_e32 v158, v158, v177
	v_fma_f32 v159, v108, s22, -v111
	v_fma_f32 v160, v108, s0, -v111
	v_max3_f32 v121, v121, v154, v155
	v_cndmask_b32_e64 v157, v216, v157, s[24:25]
	v_cndmask_b32_e64 v158, v216, v158, s[24:25]
	v_add_f32_e32 v159, v159, v178
	v_add_f32_e32 v160, v160, v179
	v_fma_f32 v161, v108, s33, -v111
	v_fma_f32 v170, v108, s61, -v111
	v_max3_f32 v121, v121, v157, v158
	v_cndmask_b32_e64 v159, v216, v159, s[26:27]
	v_cndmask_b32_e64 v160, v216, v160, s[26:27]
	v_add_f32_e32 v161, v161, v180
	v_add_f32_e32 v170, v170, v181
	v_fma_f32 v171, v108, s4, -v111
	v_fma_f32 v172, v108, s81, -v111
	v_max3_f32 v121, v121, v159, v160
	v_cndmask_b32_e64 v161, v216, v161, s[26:27]
	v_cndmask_b32_e64 v170, v216, v170, s[26:27]
	v_add_f32_e32 v171, v171, v182
	v_add_f32_e32 v172, v172, v183
	v_fma_f32 v173, v108, s69, -v111
	v_fma_f32 v174, v108, s59, -v111
	v_max3_f32 v121, v121, v161, v170
	v_cndmask_b32_e64 v171, v216, v171, s[28:29]
	v_cndmask_b32_e64 v172, v216, v172, s[28:29]
	v_add_f32_e32 v173, v173, v184
	v_add_f32_e32 v174, v174, v185
	v_fma_f32 v175, v108, s16, -v111
	v_fma_f32 v176, v108, s58, -v111
	v_max3_f32 v121, v121, v171, v172
	v_cndmask_b32_e64 v173, v216, v173, s[28:29]
	v_cndmask_b32_e64 v174, v216, v174, s[28:29]
	v_add_f32_e32 v175, v175, v186
	v_add_f32_e32 v176, v176, v187
	v_fma_f32 v177, v108, s64, -v111
	v_fma_f32 v178, v108, s3, -v111
	v_max3_f32 v121, v121, v173, v174
	v_cndmask_b32_e64 v175, v216, v175, s[30:31]
	v_cndmask_b32_e64 v176, v216, v176, s[30:31]
	v_add_f32_e32 v177, v177, v188
	v_add_f32_e32 v178, v178, v189
	v_fma_f32 v179, v108, s2, -v111
	v_fma_f32 v180, v108, s63, -v111
	v_max3_f32 v121, v121, v175, v176
	v_cndmask_b32_e64 v177, v216, v177, s[30:31]
	v_cndmask_b32_e64 v178, v216, v178, s[30:31]
	v_add_f32_e32 v179, v179, v190
	v_add_f32_e32 v180, v180, v191
	v_fma_f32 v181, v108, s82, -v111
	v_fma_f32 v182, v108, s83, -v111
	v_max3_f32 v121, v121, v177, v178
	v_cndmask_b32_e64 v179, v216, v179, s[34:35]
	v_cndmask_b32_e64 v180, v216, v180, s[34:35]
	v_add_f32_e32 v181, v181, v192
	v_add_f32_e32 v182, v182, v193
	v_fma_f32 v183, v108, s80, -v111
	v_fma_f32 v184, v108, s90, -v111
	v_max3_f32 v121, v121, v179, v180
	v_cndmask_b32_e64 v181, v216, v181, s[34:35]
	v_cndmask_b32_e64 v182, v216, v182, s[34:35]
	v_add_f32_e32 v183, v183, v194
	v_add_f32_e32 v184, v184, v195
	v_fma_f32 v185, v108, s91, -v111
	v_fma_f32 v186, v108, s88, -v111
	v_max3_f32 v121, v121, v181, v182
	v_cndmask_b32_e64 v183, v216, v183, s[36:37]
	v_cndmask_b32_e64 v184, v216, v184, s[36:37]
	v_add_f32_e32 v185, v185, v196
	v_add_f32_e32 v186, v186, v197
	v_fma_f32 v187, v108, s89, -v111
	v_fma_f32 v188, v108, s75, -v111
	v_max3_f32 v121, v121, v183, v184
	v_cndmask_b32_e64 v185, v216, v185, s[36:37]
	v_cndmask_b32_e64 v186, v216, v186, s[36:37]
	v_add_f32_e32 v187, v187, v198
	v_add_f32_e32 v188, v188, v199
	v_fma_f32 v189, v108, s96, -v111
	v_fma_f32 v190, v108, s97, -v111
	v_fma_f32 v191, v108, s5, -v111
	v_max3_f32 v121, v121, v185, v186
	v_cndmask_b32_e64 v187, v216, v187, s[38:39]
	v_cndmask_b32_e64 v188, v216, v188, s[38:39]
	v_add_f32_e32 v189, v189, v200
	v_add_f32_e32 v190, v190, v201
	v_add_f32_e32 v104, v191, v104
	v_fma_f32 v191, v108, s60, -v111
	v_fma_f32 v108, v108, s66, -v111
	v_max3_f32 v121, v121, v187, v188
	v_cndmask_b32_e64 v189, v216, v189, s[38:39]
	v_cndmask_b32_e64 v190, v216, v190, s[38:39]
	v_add_f32_e32 v105, v191, v105
	v_add_f32_e32 v106, v108, v106
	v_sub_f32_e32 v108, v110, v111
	s_and_b64 vcc, s[84:85], vcc
	v_max3_f32 v121, v121, v189, v190
	v_cndmask_b32_e64 v104, v216, v104, s[44:45]
	v_cndmask_b32_e64 v105, v216, v105, s[42:43]
	v_add_f32_e32 v107, v108, v107
	v_max3_f32 v121, v121, v104, v105
	v_cndmask_b32_e64 v106, v216, v106, s[40:41]
	v_cndmask_b32_e32 v107, v216, v107, vcc
	v_max3_f32 v108, v121, v106, v107
	ds_bpermute_b32 v110, v141, v108
	s_add_i32 s14, s14, 2
	s_add_u32 s70, s70, 0x100
	s_addc_u32 s71, s71, 0
	s_add_i32 s9, s9, 2
	s_waitcnt lgkmcnt(0)
	v_max_f32_e32 v110, v110, v110
	v_max_f32_e32 v108, v108, v110
	ds_bpermute_b32 v110, v142, v108
	s_cmp_eq_u32 s14, 4
	s_waitcnt lgkmcnt(0)
	v_max_f32_e32 v110, v110, v110
	v_max_f32_e32 v108, v108, v110
	v_sub_f32_e32 v3, v3, v108
	v_exp_f32_e32 v110, v3
	v_sub_f32_e32 v109, v109, v108
	v_exp_f32_e32 v109, v109
	v_sub_f32_e32 v111, v123, v108
	v_exp_f32_e32 v111, v111
	v_sub_f32_e32 v121, v125, v108
	v_exp_f32_e32 v191, v121
	v_sub_f32_e32 v121, v154, v108
	v_add_f32_e32 v3, 0, v110
	v_exp_f32_e32 v192, v121
	v_sub_f32_e32 v121, v155, v108
	v_add_f32_e32 v3, v109, v3
	v_exp_f32_e32 v193, v121
	v_sub_f32_e32 v121, v157, v108
	v_add_f32_e32 v3, v111, v3
	v_exp_f32_e32 v157, v121
	v_sub_f32_e32 v121, v158, v108
	v_add_f32_e32 v3, v191, v3
	v_exp_f32_e32 v158, v121
	v_sub_f32_e32 v121, v159, v108
	v_add_f32_e32 v3, v192, v3
	v_exp_f32_e32 v159, v121
	v_sub_f32_e32 v121, v160, v108
	v_add_f32_e32 v3, v193, v3
	v_exp_f32_e32 v160, v121
	v_sub_f32_e32 v121, v161, v108
	v_add_f32_e32 v3, v157, v3
	v_exp_f32_e32 v161, v121
	v_sub_f32_e32 v121, v170, v108
	v_add_f32_e32 v3, v158, v3
	v_exp_f32_e32 v198, v121
	v_sub_f32_e32 v121, v171, v108
	v_add_f32_e32 v3, v159, v3
	v_exp_f32_e32 v199, v121
	v_sub_f32_e32 v121, v172, v108
	v_add_f32_e32 v3, v160, v3
	v_exp_f32_e32 v200, v121
	v_sub_f32_e32 v121, v173, v108
	v_add_f32_e32 v3, v161, v3
	v_exp_f32_e32 v201, v121
	v_sub_f32_e32 v121, v174, v108
	v_add_f32_e32 v3, v198, v3
	v_exp_f32_e32 v202, v121
	v_sub_f32_e32 v121, v175, v108
	v_add_f32_e32 v3, v199, v3
	v_exp_f32_e32 v203, v121
	v_sub_f32_e32 v121, v176, v108
	v_add_f32_e32 v3, v200, v3
	v_exp_f32_e32 v204, v121
	v_sub_f32_e32 v121, v177, v108
	v_add_f32_e32 v3, v201, v3
	v_exp_f32_e32 v205, v121
	v_sub_f32_e32 v121, v178, v108
	v_add_f32_e32 v3, v202, v3
	v_exp_f32_e32 v206, v121
	v_sub_f32_e32 v121, v179, v108
	v_add_f32_e32 v3, v203, v3
	v_exp_f32_e32 v207, v121
	v_sub_f32_e32 v121, v180, v108
	v_add_f32_e32 v3, v204, v3
	v_exp_f32_e32 v219, v121
	v_sub_f32_e32 v121, v181, v108
	v_add_f32_e32 v3, v205, v3
	v_exp_f32_e32 v220, v121
	v_sub_f32_e32 v121, v182, v108
	v_add_f32_e32 v3, v206, v3
	v_exp_f32_e32 v221, v121
	v_sub_f32_e32 v121, v183, v108
	v_add_f32_e32 v3, v207, v3
	v_exp_f32_e32 v125, v121
	v_sub_f32_e32 v121, v184, v108
	v_add_f32_e32 v3, v219, v3
	v_exp_f32_e32 v154, v121
	v_sub_f32_e32 v121, v185, v108
	v_add_f32_e32 v3, v220, v3
	v_exp_f32_e32 v155, v121
	v_sub_f32_e32 v121, v186, v108
	v_add_f32_e32 v3, v221, v3
	v_exp_f32_e32 v222, v121
	v_sub_f32_e32 v121, v187, v108
	v_add_f32_e32 v3, v125, v3
	v_exp_f32_e32 v223, v121
	v_sub_f32_e32 v121, v188, v108
	v_add_f32_e32 v3, v154, v3
	v_exp_f32_e32 v224, v121
	v_sub_f32_e32 v121, v189, v108
	v_add_f32_e32 v3, v155, v3
	v_exp_f32_e32 v225, v121
	v_sub_f32_e32 v121, v190, v108
	v_add_f32_e32 v3, v222, v3
	v_exp_f32_e32 v226, v121
	v_sub_f32_e32 v104, v104, v108
	v_add_f32_e32 v3, v223, v3
	v_exp_f32_e32 v104, v104
	v_sub_f32_e32 v105, v105, v108
	v_add_f32_e32 v3, v224, v3
	v_exp_f32_e32 v105, v105
	v_sub_f32_e32 v106, v106, v108
	v_add_f32_e32 v3, v225, v3
	v_exp_f32_e32 v106, v106
	v_sub_f32_e32 v107, v107, v108
	v_add_f32_e32 v3, v226, v3
	v_exp_f32_e32 v107, v107
	v_add_f32_e32 v3, v104, v3
	v_add_f32_e32 v3, v105, v3
	v_add_f32_e32 v3, v106, v3
	v_add_f32_e32 v3, v107, v3
	ds_bpermute_b32 v121, v141, v3
	v_fma_f32 v1, v1, s65, -v108
	v_lshlrev_b32_e32 v108, 1, v0
	v_and_b32_e32 v174, 3, v0
	v_cvt_pk_bf16_f32 v0, v104, v105
	v_and_or_b32 v104, v108, s67, v174
	v_mul_lo_u32 v104, v104, s94
	v_cvt_pk_bf16_f32 v173, v157, v158
	v_add3_u32 v157, v143, v130, v104
	v_add_u32_e32 v158, 0x9000, v157
	s_waitcnt lgkmcnt(0)
	v_add_f32_e32 v3, v3, v121
	v_exp_f32_e32 v121, v1
	v_cvt_pk_bf16_f32 v1, v106, v107
	ds_read2_b64 v[104:107], v158 offset1:4
	v_cvt_pk_bf16_f32 v170, v110, v109
	v_cvt_pk_bf16_f32 v171, v111, v191
	v_cvt_pk_bf16_f32 v172, v192, v193
	v_add_u32_e32 v227, 0x9800, v157
	ds_read2_b64 v[178:181], v227 offset0:12 offset1:16
	s_waitcnt lgkmcnt(1)
	v_mfma_f32_16x16x32_bf16 v[174:177], v[104:107], v[170:173], 0
	v_add_u32_e32 v104, 0x9100, v157
	ds_read2_b64 v[108:111], v104 offset1:232
	s_waitcnt lgkmcnt(1)
	v_mov_b32_e32 v106, v178
	v_mov_b32_e32 v107, v179
	v_mov_b32_e32 v178, v180
	v_mov_b32_e32 v179, v181
	s_waitcnt lgkmcnt(0)
	v_mov_b32_e32 v104, v110
	v_mov_b32_e32 v105, v111
	v_add_u32_e32 v110, 0xd000, v157
	v_add_u32_e32 v111, 0xd800, v157
	v_mfma_f32_16x16x32_bf16 v[182:185], v[104:107], v[170:173], 0
	ds_read2_b64 v[104:107], v110 offset0:64 offset1:68
	ds_read2_b64 v[190:193], v111 offset0:76 offset1:80
	ds_bpermute_b32 v123, v142, v3
	s_waitcnt lgkmcnt(2)
	v_mfma_f32_16x16x32_bf16 v[186:189], v[104:107], v[170:173], 0
	v_add_u32_e32 v104, 0xd300, v157
	ds_read2_b64 v[104:107], v104 offset1:232
	s_waitcnt lgkmcnt(2)
	v_mov_b32_e32 v196, v190
	v_mov_b32_e32 v197, v191
	v_mov_b32_e32 v190, v192
	v_mov_b32_e32 v191, v193
	s_waitcnt lgkmcnt(0)
	v_mov_b32_e32 v194, v106
	v_mov_b32_e32 v195, v107
	v_mov_b32_e32 v106, v104
	v_mov_b32_e32 v107, v105
	v_mfma_f32_16x16x32_bf16 v[170:173], v[194:197], v[170:173], 0
	v_cvt_pk_bf16_f32 v195, v161, v198
	v_cvt_pk_bf16_f32 v196, v199, v200
	v_cvt_pk_bf16_f32 v197, v201, v202
	ds_read2_b64 v[198:201], v158 offset0:8 offset1:12
	v_cvt_pk_bf16_f32 v194, v159, v160
	v_add_f32_e32 v123, v3, v123
	v_mov_b32_e32 v3, v2
	s_waitcnt lgkmcnt(0)
	v_mfma_f32_16x16x32_bf16 v[174:177], v[198:201], v[194:197], v[174:177]
	ds_read2_b64 v[198:201], v227 offset0:20 offset1:24
	v_lshl_add_u64 v[130:131], v[130:131], 1, v[132:133]
	s_waitcnt lgkmcnt(0)
	v_mov_b32_e32 v180, v198
	v_mov_b32_e32 v181, v199
	v_mov_b32_e32 v198, v200
	v_mov_b32_e32 v199, v201
	v_mfma_f32_16x16x32_bf16 v[178:181], v[178:181], v[194:197], v[182:185]
	s_nop 2
	ds_read2_b64 v[182:185], v110 offset0:72 offset1:76
	s_waitcnt lgkmcnt(0)
	v_mfma_f32_16x16x32_bf16 v[182:185], v[182:185], v[194:197], v[186:189]
	s_nop 2
	ds_read2_b64 v[186:189], v111 offset0:84 offset1:88
	s_waitcnt lgkmcnt(0)
	v_mov_b32_e32 v192, v186
	v_mov_b32_e32 v193, v187
	v_mov_b32_e32 v186, v188
	v_mov_b32_e32 v187, v189
	v_mfma_f32_16x16x32_bf16 v[170:173], v[190:193], v[194:197], v[170:173]
	ds_read2_b64 v[194:197], v158 offset0:16 offset1:20
	v_cvt_pk_bf16_f32 v190, v203, v204
	v_cvt_pk_bf16_f32 v191, v205, v206
	v_cvt_pk_bf16_f32 v192, v207, v219
	v_cvt_pk_bf16_f32 v193, v220, v221
	s_waitcnt lgkmcnt(0)
	s_nop 0
	v_mfma_f32_16x16x32_bf16 v[174:177], v[194:197], v[190:193], v[174:177]
	ds_read2_b64 v[194:197], v227 offset0:28 offset1:32
	s_waitcnt lgkmcnt(0)
	v_mov_b32_e32 v200, v194
	v_mov_b32_e32 v201, v195
	v_mov_b32_e32 v194, v196
	v_mov_b32_e32 v195, v197
	v_mfma_f32_16x16x32_bf16 v[178:181], v[198:201], v[190:193], v[178:181]
	ds_read2_b64 v[198:201], v110 offset0:80 offset1:84
	s_waitcnt lgkmcnt(0)
	v_mfma_f32_16x16x32_bf16 v[182:185], v[198:201], v[190:193], v[182:185]
	ds_read2_b64 v[198:201], v111 offset0:92 offset1:96
	s_waitcnt lgkmcnt(0)
	v_mov_b32_e32 v188, v198
	v_mov_b32_e32 v189, v199
	v_mov_b32_e32 v198, v200
	v_mov_b32_e32 v199, v201
	v_mfma_f32_16x16x32_bf16 v[170:173], v[186:189], v[190:193], v[170:173]
	ds_read2_b64 v[190:193], v158 offset0:24 offset1:28
	v_cvt_pk_bf16_f32 v186, v125, v154
	v_cvt_pk_bf16_f32 v187, v155, v222
	v_cvt_pk_bf16_f32 v188, v223, v224
	v_cvt_pk_bf16_f32 v189, v225, v226
	s_waitcnt lgkmcnt(0)
	s_nop 0
	v_mfma_f32_16x16x32_bf16 v[174:177], v[190:193], v[186:189], v[174:177]
	ds_read2_b64 v[190:193], v227 offset0:36 offset1:40
	s_waitcnt lgkmcnt(0)
	v_mov_b32_e32 v196, v190
	v_mov_b32_e32 v197, v191
	v_mov_b32_e32 v190, v192
	v_mov_b32_e32 v191, v193
	v_mfma_f32_16x16x32_bf16 v[178:181], v[194:197], v[186:189], v[178:181]
	ds_read2_b64 v[194:197], v110 offset0:88 offset1:92
	v_mov_b32_e32 v110, v108
	s_waitcnt lgkmcnt(0)
	v_mfma_f32_16x16x32_bf16 v[182:185], v[194:197], v[186:189], v[182:185]
	ds_read2_b64 v[194:197], v111 offset0:100 offset1:104
	v_mov_b32_e32 v111, v109
	s_waitcnt lgkmcnt(0)
	v_mov_b32_e32 v200, v194
	v_mov_b32_e32 v201, v195
	v_mov_b32_e32 v194, v196
	v_mov_b32_e32 v195, v197
	v_mfma_f32_16x16x32_bf16 v[170:173], v[198:201], v[186:189], v[170:173]
	v_mfma_f32_16x16x32_bf16 v[108:111], v[108:111], v[0:3], v[174:177]
	v_mfma_f32_16x16x32_bf16 v[174:177], v[190:193], v[0:3], v[178:181]
	v_mfma_f32_16x16x32_bf16 v[104:107], v[104:107], v[0:3], v[182:185]
	v_mfma_f32_16x16x32_bf16 v[170:173], v[194:197], v[0:3], v[170:173]
	v_add_f32_e32 v0, v121, v123
	v_div_scale_f32 v1, s[40:41], v0, v0, 1.0
	v_rcp_f32_e32 v3, v1
	s_mov_b64 s[40:41], 0x7e00400
	v_lshl_add_u64 v[132:133], v[130:131], 0, s[40:41]
	v_fma_f32 v121, -v1, v3, 1.0
	v_fmac_f32_e32 v3, v121, v3
	v_div_scale_f32 v121, vcc, 1.0, v0, 1.0
	v_mul_f32_e32 v123, v121, v3
	v_fma_f32 v125, -v1, v123, v121
	v_fmac_f32_e32 v123, v125, v3
	v_fma_f32 v1, -v1, v123, v121
	v_div_fmas_f32 v1, v1, v3, v123
	v_div_fixup_f32 v0, v1, v0, 1.0
	v_pk_mul_f32 v[108:109], v[108:109], v[0:1] op_sel_hi:[1,0]
	v_pk_mul_f32 v[110:111], v[110:111], v[0:1] op_sel_hi:[1,0]
	v_pk_mul_f32 v[104:105], v[104:105], v[0:1] op_sel_hi:[1,0]
	v_pk_mul_f32 v[106:107], v[106:107], v[0:1] op_sel_hi:[1,0]
	v_cvt_pk_bf16_f32 v108, v108, v109
	v_cvt_pk_bf16_f32 v109, v110, v111
	v_pk_mul_f32 v[110:111], v[174:175], v[0:1] op_sel_hi:[1,0]
	v_pk_mul_f32 v[134:135], v[176:177], v[0:1] op_sel_hi:[1,0]
	v_add_co_u32_e32 v130, vcc, s74, v130
	v_cvt_pk_bf16_f32 v104, v104, v105
	v_cvt_pk_bf16_f32 v105, v106, v107
	v_pk_mul_f32 v[106:107], v[170:171], v[0:1] op_sel_hi:[1,0]
	v_pk_mul_f32 v[0:1], v[172:173], v[0:1] op_sel_hi:[1,0]
	v_cvt_pk_bf16_f32 v110, v110, v111
	v_cvt_pk_bf16_f32 v111, v134, v135
	v_addc_co_u32_e32 v131, vcc, 0, v131, vcc
	v_cvt_pk_bf16_f32 v106, v106, v107
	v_cvt_pk_bf16_f32 v107, v0, v1
	global_store_dwordx4 v[130:131], v[108:111], off offset:1024 nt
	global_store_dwordx4 v[132:133], v[104:107], off offset:64 nt
	s_cbranch_scc1 .LBB0_425
.LBB0_429:
	s_waitcnt vmcnt(3)
	v_lshlrev_b32_e32 v170, 16, v96
	v_and_b32_e32 v171, 0xffff0000, v96
	v_lshlrev_b32_e32 v158, 16, v97
	v_and_b32_e32 v159, 0xffff0000, v97
	v_pk_mul_f32 v[96:97], v[170:171], v[170:171]
	v_pk_mul_f32 v[160:161], v[158:159], v[158:159]
	v_add_f32_e32 v3, v96, v97
	v_lshlrev_b32_e32 v154, 16, v98
	v_and_b32_e32 v155, 0xffff0000, v98
	v_add_f32_e32 v3, v160, v3
	v_lshlrev_b32_e32 v132, 16, v99
	v_and_b32_e32 v133, 0xffff0000, v99
	v_pk_mul_f32 v[98:99], v[154:155], v[154:155]
	v_add_f32_e32 v3, v161, v3
	v_add_f32_e32 v3, v98, v3
	v_pk_mul_f32 v[134:135], v[132:133], v[132:133]
	v_add_f32_e32 v3, v99, v3
	s_waitcnt vmcnt(2)
	v_lshlrev_b32_e32 v130, 16, v100
	v_and_b32_e32 v131, 0xffff0000, v100
	v_add_f32_e32 v3, v134, v3
	v_lshlrev_b32_e32 v110, 16, v101
	v_and_b32_e32 v111, 0xffff0000, v101
	v_pk_mul_f32 v[100:101], v[130:131], v[130:131]
	v_add_f32_e32 v3, v135, v3
	v_add_f32_e32 v3, v100, v3
	v_pk_mul_f32 v[106:107], v[110:111], v[110:111]
	v_add_f32_e32 v3, v101, v3
	v_lshlrev_b32_e32 v108, 16, v102
	v_and_b32_e32 v109, 0xffff0000, v102
	v_add_f32_e32 v3, v106, v3
	v_lshlrev_b32_e32 v0, 16, v103
	v_and_b32_e32 v1, 0xffff0000, v103
	v_pk_mul_f32 v[102:103], v[108:109], v[108:109]
	v_add_f32_e32 v3, v107, v3
	v_add_f32_e32 v3, v102, v3
	v_pk_mul_f32 v[104:105], v[0:1], v[0:1]
	v_add_f32_e32 v3, v103, v3
	v_add_f32_e32 v3, v104, v3
	v_add_f32_e32 v3, v105, v3
	ds_bpermute_b32 v96, v141, v3
	s_add_u32 s72, s12, s70
	s_addc_u32 s73, s13, s71
	s_add_i32 s40, s9, -1
	s_waitcnt lgkmcnt(0)
	v_add_f32_e32 v3, v3, v96
	ds_bpermute_b32 v96, v142, v3
	s_waitcnt lgkmcnt(0)
	v_add_f32_e32 v3, v3, v96
	v_fmamk_f32 v3, v3, 0x3c800000, v209
	v_mul_f32_e32 v96, 0x4b800000, v3
	v_cmp_gt_f32_e32 vcc, s68, v3
	s_nop 1
	v_cndmask_b32_e32 v3, v3, v96, vcc
	v_rsq_f32_e32 v3, v3
	s_nop 0
	v_mul_f32_e32 v96, 0x45800000, v3
	v_cndmask_b32_e32 v3, v3, v96, vcc
	v_mul_f32_e32 v100, 0x3e38aa3b, v3
	v_pk_mul_f32 v[96:97], v[100:101], v[170:171] op_sel_hi:[0,1]
	s_waitcnt vmcnt(4)
	v_pk_mul_f32 v[96:97], v[4:5], v[96:97]
	v_pk_mul_f32 v[0:1], v[100:101], v[0:1] op_sel_hi:[0,1]
	v_cvt_pk_bf16_f32 v102, v96, v97
	v_pk_mul_f32 v[96:97], v[100:101], v[158:159] op_sel_hi:[0,1]
	v_pk_mul_f32 v[96:97], v[6:7], v[96:97]
	s_waitcnt vmcnt(1)
	v_pk_mul_f32 v[0:1], v[18:19], v[0:1]
	v_cvt_pk_bf16_f32 v103, v96, v97
	v_pk_mul_f32 v[96:97], v[100:101], v[154:155] op_sel_hi:[0,1]
	v_pk_mul_f32 v[96:97], v[8:9], v[96:97]
	v_mov_b32_e32 v3, v113
	v_cvt_pk_bf16_f32 v104, v96, v97
	v_pk_mul_f32 v[96:97], v[100:101], v[132:133] op_sel_hi:[0,1]
	v_pk_mul_f32 v[96:97], v[10:11], v[96:97]
	s_nop 0
	v_cvt_pk_bf16_f32 v105, v96, v97
	v_pk_mul_f32 v[96:97], v[100:101], v[130:131] op_sel_hi:[0,1]
	v_pk_mul_f32 v[96:97], v[12:13], v[96:97]
	v_mfma_f32_16x16x32_bf16 v[194:197], v[80:83], v[102:105], 0
	v_cvt_pk_bf16_f32 v106, v96, v97
	v_pk_mul_f32 v[96:97], v[100:101], v[110:111] op_sel_hi:[0,1]
	v_pk_mul_f32 v[96:97], v[14:15], v[96:97]
	s_nop 0
	v_cvt_pk_bf16_f32 v107, v96, v97
	v_pk_mul_f32 v[96:97], v[100:101], v[108:109] op_sel_hi:[0,1]
	v_pk_mul_f32 v[96:97], v[16:17], v[96:97]
	v_cvt_pk_bf16_f32 v109, v0, v1
	v_cvt_pk_bf16_f32 v108, v96, v97
	v_mfma_f32_16x16x32_bf16 v[96:99], v[24:27], v[102:105], 0
	v_mov_b32_e32 v100, v112
	v_mfma_f32_16x16x32_bf16 v[130:133], v[28:31], v[106:109], v[96:99]
	v_lshlrev_b32_e32 v0, 3, v3
	v_ashrrev_i32_e32 v1, 31, v0
	v_ashrrev_i32_e32 v101, 31, v100
	v_mfma_f32_16x16x32_bf16 v[96:99], v[32:35], v[102:105], 0
	v_lshlrev_b32_e32 v3, 2, v3
	v_sub_u32_e32 v3, v100, v3
	v_cmp_gt_i32_e64 s[48:49], 0, v3
	v_mfma_f32_16x16x32_bf16 v[170:173], v[36:39], v[106:109], v[96:99]
	v_cmp_gt_i32_e64 s[50:51], 1, v3
	v_cmp_gt_i32_e64 s[52:53], 2, v3
	v_cmp_gt_i32_e64 s[54:55], 3, v3
	v_mfma_f32_16x16x32_bf16 v[96:99], v[40:43], v[102:105], 0
	v_cmp_lt_i32_e64 s[44:45], -1, v3
	v_cmp_lt_i32_e64 s[42:43], 0, v3
	v_mfma_f32_16x16x32_bf16 v[174:177], v[44:47], v[106:109], v[96:99]
	v_mfma_f32_16x16x32_bf16 v[96:99], v[48:51], v[102:105], 0
	v_mfma_f32_16x16x32_bf16 v[178:181], v[52:55], v[106:109], v[96:99]
	v_mfma_f32_16x16x32_bf16 v[96:99], v[56:59], v[102:105], 0
	v_mfma_f32_16x16x32_bf16 v[182:185], v[60:63], v[106:109], v[96:99]
	v_mfma_f32_16x16x32_bf16 v[96:99], v[64:67], v[102:105], 0
	v_mfma_f32_16x16x32_bf16 v[186:189], v[68:71], v[106:109], v[96:99]
	v_mfma_f32_16x16x32_bf16 v[96:99], v[72:75], v[102:105], 0
	v_mfma_f32_16x16x32_bf16 v[190:193], v[76:79], v[106:109], v[96:99]
	v_mfma_f32_16x16x32_bf16 v[102:105], v[88:91], v[102:105], 0
	s_nop 5
	v_lshlrev_b64 v[98:99], 1, v[0:1]
	v_cvt_f32_u32_e32 v1, s40
	v_lshl_add_u64 v[96:97], v[126:127], 0, v[100:101]
	v_mad_u64_u32 v[110:111], s[40:41], v96, s62, v[98:99]
	v_cmp_lt_f32_e32 vcc, s57, v1
	s_and_b64 s[40:41], vcc, exec
	s_cselect_b32 s40, 0xffffffc0, 0
	v_cndmask_b32_e32 v101, 0, v215, vcc
	v_sub_f32_e32 v1, v101, v1
	v_exp_f32_e32 v1, v1
	v_cmp_lt_i32_e32 vcc, 2, v3
	s_cmp_eq_u32 s70, 0
	v_mfma_f32_16x16x32_bf16 v[194:197], v[84:87], v[106:109], v[194:197]
	v_ldexp_f32 v1, v1, s40
	v_cmp_lt_i32_e64 s[40:41], 1, v3
	v_add_u32_e32 v3, 0x80, v3
	v_cvt_f32_i32_e32 v157, v3
	v_mfma_f32_16x16x32_bf16 v[102:105], v[92:95], v[106:109], v[102:105]
	v_mul_f32_e32 v106, 0x3fb8aa3b, v1
	s_cselect_b64 s[46:47], -1, 0
	s_cmp_eq_u32 s14, 2
	s_cselect_b64 s[56:57], -1, 0
	v_pk_mul_f32 v[108:109], v[106:107], v[156:157] op_sel_hi:[0,1]
	s_waitcnt vmcnt(0)
	v_cndmask_b32_e64 v3, v23, v22, s[56:57]
	v_fma_f32 v107, v106, 0, -v109
	v_cndmask_b32_e64 v101, v3, v20, s[46:47]
	v_add_f32_e32 v107, v107, v130
	s_and_b64 s[46:47], s[78:79], s[48:49]
	v_fma_f32 v1, v1, s65, -v109
	v_cndmask_b32_e64 v121, v216, v107, s[46:47]
	v_add_f32_e32 v1, v1, v131
	s_and_b64 s[46:47], s[78:79], s[50:51]
	v_fma_f32 v107, v106, 2.0, -v109
	v_cndmask_b32_e64 v1, v216, v1, s[46:47]
	v_add_f32_e32 v107, v107, v132
	s_and_b64 s[46:47], s[78:79], s[52:53]
	v_cndmask_b32_e64 v123, v216, v107, s[46:47]
	v_fma_f32 v107, v106, s17, -v109
	v_add_f32_e32 v107, v107, v133
	s_and_b64 s[46:47], s[78:79], s[54:55]
	v_cndmask_b32_e64 v125, v216, v107, s[46:47]
	v_fma_f32 v107, v106, s18, -v109
	v_add_f32_e32 v107, v107, v170
	v_cndmask_b32_e64 v130, v216, v107, s[24:25]
	v_fma_f32 v107, v106, s19, -v109
	v_add_f32_e32 v107, v107, v171
	v_cndmask_b32_e64 v131, v216, v107, s[24:25]
	v_fma_f32 v107, v106, s20, -v109
	v_add_f32_e32 v107, v107, v172
	v_cndmask_b32_e64 v132, v216, v107, s[24:25]
	v_fma_f32 v107, v106, s21, -v109
	v_add_f32_e32 v107, v107, v173
	v_cndmask_b32_e64 v133, v216, v107, s[24:25]
	v_fma_f32 v107, v106, s22, -v109
	v_add_f32_e32 v107, v107, v174
	v_cndmask_b32_e64 v135, v216, v107, s[26:27]
	v_fma_f32 v107, v106, s0, -v109
	v_add_f32_e32 v107, v107, v175
	v_cndmask_b32_e64 v154, v216, v107, s[26:27]
	v_fma_f32 v107, v106, s33, -v109
	v_add_f32_e32 v107, v107, v176
	v_cndmask_b32_e64 v155, v216, v107, s[26:27]
	v_fma_f32 v107, v106, s61, -v109
	v_add_f32_e32 v107, v107, v177
	v_cndmask_b32_e64 v157, v216, v107, s[26:27]
	v_fma_f32 v107, v106, s4, -v109
	v_add_f32_e32 v107, v107, v178
	v_cndmask_b32_e64 v158, v216, v107, s[28:29]
	v_fma_f32 v107, v106, s81, -v109
	v_add_f32_e32 v107, v107, v179
	v_cndmask_b32_e64 v159, v216, v107, s[28:29]
	v_fma_f32 v107, v106, s69, -v109
	v_add_f32_e32 v107, v107, v180
	v_cndmask_b32_e64 v160, v216, v107, s[28:29]
	v_fma_f32 v107, v106, s59, -v109
	v_add_f32_e32 v107, v107, v181
	v_cndmask_b32_e64 v161, v216, v107, s[28:29]
	v_fma_f32 v107, v106, s16, -v109
	v_add_f32_e32 v107, v107, v182
	v_cndmask_b32_e64 v170, v216, v107, s[30:31]
	v_fma_f32 v107, v106, s58, -v109
	v_add_f32_e32 v107, v107, v183
	v_cndmask_b32_e64 v171, v216, v107, s[30:31]
	v_fma_f32 v107, v106, s64, -v109
	v_add_f32_e32 v107, v107, v184
	v_cndmask_b32_e64 v172, v216, v107, s[30:31]
	v_fma_f32 v107, v106, s3, -v109
	v_add_f32_e32 v107, v107, v185
	v_cndmask_b32_e64 v173, v216, v107, s[30:31]
	v_fma_f32 v107, v106, s2, -v109
	v_add_f32_e32 v107, v107, v186
	v_cndmask_b32_e64 v174, v216, v107, s[34:35]
	v_fma_f32 v107, v106, s63, -v109
	v_add_f32_e32 v107, v107, v187
	v_cndmask_b32_e64 v175, v216, v107, s[34:35]
	v_fma_f32 v107, v106, s82, -v109
	v_add_f32_e32 v107, v107, v188
	v_cndmask_b32_e64 v176, v216, v107, s[34:35]
	v_fma_f32 v107, v106, s83, -v109
	v_add_f32_e32 v107, v107, v189
	v_cndmask_b32_e64 v177, v216, v107, s[34:35]
	v_fma_f32 v107, v106, s80, -v109
	v_add_f32_e32 v107, v107, v190
	v_cndmask_b32_e64 v178, v216, v107, s[36:37]
	v_fma_f32 v107, v106, s90, -v109
	v_add_f32_e32 v107, v107, v191
	v_cndmask_b32_e64 v179, v216, v107, s[36:37]
	v_fma_f32 v107, v106, s91, -v109
	v_add_f32_e32 v107, v107, v192
	v_cndmask_b32_e64 v180, v216, v107, s[36:37]
	v_fma_f32 v107, v106, s88, -v109
	v_mul_f32_e32 v3, 0x3fb8aa3b, v101
	v_add_f32_e32 v107, v107, v193
	v_max3_f32 v3, v3, v121, v1
	v_cndmask_b32_e64 v181, v216, v107, s[36:37]
	v_fma_f32 v107, v106, s89, -v109
	v_max3_f32 v3, v3, v123, v125
	v_add_f32_e32 v107, v107, v194
	v_max3_f32 v3, v3, v130, v131
	v_cndmask_b32_e64 v182, v216, v107, s[38:39]
	v_fma_f32 v107, v106, s75, -v109
	v_max3_f32 v3, v3, v132, v133
	v_add_f32_e32 v107, v107, v195
	v_max3_f32 v3, v3, v135, v154
	v_cndmask_b32_e64 v183, v216, v107, s[38:39]
	v_fma_f32 v107, v106, s96, -v109
	v_max3_f32 v3, v3, v155, v157
	v_add_f32_e32 v107, v107, v196
	v_max3_f32 v3, v3, v158, v159
	v_cndmask_b32_e64 v184, v216, v107, s[38:39]
	v_fma_f32 v107, v106, s97, -v109
	v_max3_f32 v3, v3, v160, v161
	v_add_f32_e32 v107, v107, v197
	v_max3_f32 v3, v3, v170, v171
	v_cndmask_b32_e64 v185, v216, v107, s[38:39]
	v_fma_f32 v107, v106, s5, -v109
	v_max3_f32 v3, v3, v172, v173
	v_add_f32_e32 v102, v107, v102
	s_and_b64 s[44:45], s[84:85], s[44:45]
	v_max3_f32 v3, v3, v174, v175
	v_cndmask_b32_e64 v186, v216, v102, s[44:45]
	v_fma_f32 v102, v106, s60, -v109
	v_max3_f32 v3, v3, v176, v177
	v_add_f32_e32 v102, v102, v103
	s_and_b64 s[42:43], s[84:85], s[42:43]
	v_max3_f32 v3, v3, v178, v179
	v_cndmask_b32_e64 v198, v216, v102, s[42:43]
	v_fma_f32 v102, v106, s66, -v109
	v_max3_f32 v3, v3, v180, v181
	v_add_f32_e32 v102, v102, v104
	s_and_b64 s[40:41], s[84:85], s[40:41]
	v_max3_f32 v3, v3, v182, v183
	v_cndmask_b32_e64 v206, v216, v102, s[40:41]
	v_sub_f32_e32 v102, v108, v109
	v_max3_f32 v3, v3, v184, v185
	v_add_f32_e32 v102, v102, v105
	s_and_b64 vcc, s[84:85], vcc
	v_max3_f32 v3, v3, v186, v198
	v_cndmask_b32_e32 v207, v216, v102, vcc
	v_max3_f32 v3, v3, v206, v207
	ds_bpermute_b32 v104, v141, v3
	v_mov_b32_e32 v134, v111
	v_mad_u64_u32 v[102:103], s[40:41], v97, s62, v[134:135]
	v_mov_b32_e32 v111, v102
	s_waitcnt lgkmcnt(0)
	v_max_f32_e32 v104, v104, v104
	v_max_f32_e32 v3, v3, v104
	ds_bpermute_b32 v134, v142, v3
	v_lshl_add_u64 v[102:103], s[72:73], 0, v[110:111]
	s_mov_b32 s40, 0xbe00000
	v_add_co_u32_e32 v102, vcc, s40, v102
	v_lshlrev_b64 v[96:97], 11, v[96:97]
	s_nop 0
	v_addc_co_u32_e32 v103, vcc, 0, v103, vcc
	global_load_dwordx4 v[104:107], v[102:103], off offset:3200
	global_load_dwordx4 v[108:111], v[102:103], off offset:3264
	s_waitcnt lgkmcnt(0)
	v_max_f32_e32 v102, v134, v134
	v_max_f32_e32 v102, v3, v102
	v_sub_f32_e32 v3, v121, v102
	v_sub_f32_e32 v121, v125, v102
	v_sub_f32_e32 v125, v130, v102
	v_sub_f32_e32 v130, v131, v102
	v_exp_f32_e32 v134, v130
	v_sub_f32_e32 v130, v132, v102
	v_exp_f32_e32 v187, v130
	v_sub_f32_e32 v130, v133, v102
	v_exp_f32_e32 v188, v130
	v_sub_f32_e32 v130, v135, v102
	v_exp_f32_e32 v135, v130
	v_sub_f32_e32 v130, v154, v102
	v_exp_f32_e32 v154, v130
	v_sub_f32_e32 v130, v155, v102
	v_exp_f32_e32 v155, v130
	v_sub_f32_e32 v130, v157, v102
	v_exp_f32_e32 v157, v130
	v_sub_f32_e32 v130, v158, v102
	v_exp_f32_e32 v158, v130
	v_sub_f32_e32 v130, v159, v102
	v_exp_f32_e32 v159, v130
	v_sub_f32_e32 v130, v160, v102
	v_exp_f32_e32 v160, v130
	v_sub_f32_e32 v130, v161, v102
	v_exp_f32_e32 v161, v130
	v_sub_f32_e32 v130, v170, v102
	v_exp_f32_e32 v219, v130
	v_sub_f32_e32 v130, v171, v102
	v_exp_f32_e32 v224, v130
	v_sub_f32_e32 v130, v172, v102
	v_exp_f32_e32 v225, v130
	v_sub_f32_e32 v130, v173, v102
	v_exp_f32_e32 v226, v130
	v_sub_f32_e32 v130, v174, v102
	v_exp_f32_e32 v227, v130
	v_sub_f32_e32 v130, v175, v102
	v_exp_f32_e32 v228, v130
	v_sub_f32_e32 v130, v176, v102
	v_exp_f32_e32 v229, v130
	v_sub_f32_e32 v130, v177, v102
	v_exp_f32_e32 v230, v130
	v_sub_f32_e32 v130, v178, v102
	v_exp_f32_e32 v231, v130
	v_sub_f32_e32 v130, v179, v102
	v_exp_f32_e32 v232, v130
	v_sub_f32_e32 v130, v180, v102
	v_exp_f32_e32 v233, v130
	v_sub_f32_e32 v130, v181, v102
	v_exp_f32_e32 v234, v130
	v_sub_f32_e32 v130, v182, v102
	v_exp_f32_e32 v235, v130
	v_sub_f32_e32 v130, v183, v102
	v_exp_f32_e32 v3, v3
	v_sub_f32_e32 v1, v1, v102
	v_exp_f32_e32 v236, v130
	v_sub_f32_e32 v130, v184, v102
	v_exp_f32_e32 v1, v1
	v_sub_f32_e32 v103, v123, v102
	v_exp_f32_e32 v237, v130
	v_sub_f32_e32 v130, v185, v102
	v_exp_f32_e32 v103, v103
	v_exp_f32_e32 v238, v130
	v_sub_f32_e32 v130, v186, v102
	v_exp_f32_e32 v121, v121
	v_exp_f32_e32 v239, v130
	v_lshlrev_b32_e32 v130, 1, v100
	v_and_b32_e32 v100, 3, v100
	v_add_f32_e32 v123, 0, v3
	v_exp_f32_e32 v125, v125
	v_and_or_b32 v100, v130, s67, v100
	v_add_f32_e32 v123, v1, v123
	v_mul_lo_u32 v100, v100, s94
	v_add_f32_e32 v123, v103, v123
	v_add3_u32 v0, v143, v0, v100
	v_add_f32_e32 v123, v121, v123
	v_add_u32_e32 v100, 0x9000, v0
	v_add_f32_e32 v123, v125, v123
	ds_read2_b64 v[130:133], v100 offset1:4
	v_add_f32_e32 v123, v134, v123
	v_cvt_pk_bf16_f32 v170, v3, v1
	v_add_u32_e32 v1, 0x9100, v0
	v_add_f32_e32 v123, v187, v123
	v_cvt_pk_bf16_f32 v171, v103, v121
	ds_read2_b64 v[174:177], v1 offset1:232
	v_add_u32_e32 v1, 0x9800, v0
	v_add_u32_e32 v3, 0xd000, v0
	v_add_u32_e32 v103, 0xd300, v0
	v_add_u32_e32 v0, 0xd800, v0
	v_add_f32_e32 v123, v188, v123
	ds_read2_b64 v[178:181], v1 offset0:12 offset1:16
	v_cvt_pk_bf16_f32 v173, v187, v188
	ds_read2_b64 v[182:185], v3 offset0:64 offset1:68
	ds_read2_b64 v[186:189], v103 offset1:232
	ds_read2_b64 v[190:193], v0 offset0:76 offset1:80
	ds_read2_b64 v[194:197], v100 offset0:8 offset1:12
	v_cvt_pk_bf16_f32 v172, v125, v134
	v_sub_f32_e32 v121, v198, v102
	ds_read2_b64 v[198:201], v1 offset0:20 offset1:24
	s_waitcnt lgkmcnt(7)
	v_mfma_f32_16x16x32_bf16 v[130:133], v[130:133], v[170:173], 0
	v_add_f32_e32 v123, v135, v123
	v_add_f32_e32 v123, v154, v123
	v_add_f32_e32 v123, v155, v123
	s_waitcnt lgkmcnt(5)
	v_mfma_f32_16x16x32_bf16 v[176:179], v[176:179], v[170:173], 0
	v_add_f32_e32 v123, v157, v123
	v_add_f32_e32 v123, v158, v123
	v_add_f32_e32 v123, v159, v123
	s_waitcnt lgkmcnt(4)
	v_mfma_f32_16x16x32_bf16 v[182:185], v[182:185], v[170:173], 0
	v_add_f32_e32 v123, v160, v123
	ds_read2_b64 v[220:223], v0 offset0:84 offset1:88
	v_add_f32_e32 v123, v161, v123
	s_waitcnt lgkmcnt(3)
	v_mfma_f32_16x16x32_bf16 v[170:173], v[188:191], v[170:173], 0
	v_cvt_pk_bf16_f32 v188, v135, v154
	v_cvt_pk_bf16_f32 v189, v155, v157
	v_cvt_pk_bf16_f32 v190, v158, v159
	v_cvt_pk_bf16_f32 v191, v160, v161
	ds_read2_b64 v[202:205], v3 offset0:72 offset1:76
	v_add_f32_e32 v123, v219, v123
	s_waitcnt lgkmcnt(3)
	v_mfma_f32_16x16x32_bf16 v[130:133], v[194:197], v[188:191], v[130:133]
	v_mov_b32_e32 v194, v180
	v_mov_b32_e32 v195, v181
	s_waitcnt lgkmcnt(2)
	v_mov_b32_e32 v196, v198
	v_mov_b32_e32 v197, v199
	v_add_f32_e32 v123, v224, v123
	v_add_f32_e32 v123, v225, v123
	v_mfma_f32_16x16x32_bf16 v[176:179], v[194:197], v[188:191], v[176:179]
	ds_read2_b64 v[196:199], v100 offset0:16 offset1:20
	v_add_f32_e32 v123, v226, v123
	s_waitcnt lgkmcnt(2)
	v_mov_b32_e32 v194, v220
	v_mov_b32_e32 v195, v221
	v_add_f32_e32 v123, v227, v123
	v_add_f32_e32 v123, v228, v123
	v_add_f32_e32 v123, v229, v123
	v_add_f32_e32 v123, v230, v123
	v_add_f32_e32 v123, v231, v123
	s_waitcnt lgkmcnt(1)
	v_mfma_f32_16x16x32_bf16 v[180:183], v[202:205], v[188:191], v[182:185]
	v_add_f32_e32 v123, v232, v123
	v_add_f32_e32 v123, v233, v123
	v_add_f32_e32 v123, v234, v123
	v_mfma_f32_16x16x32_bf16 v[170:173], v[192:195], v[188:191], v[170:173]
	v_cvt_pk_bf16_f32 v188, v219, v224
	v_cvt_pk_bf16_f32 v189, v225, v226
	v_cvt_pk_bf16_f32 v190, v227, v228
	v_cvt_pk_bf16_f32 v191, v229, v230
	ds_read2_b64 v[192:195], v1 offset0:28 offset1:32
	v_add_f32_e32 v123, v235, v123
	s_waitcnt lgkmcnt(1)
	v_mfma_f32_16x16x32_bf16 v[130:133], v[196:199], v[188:191], v[130:133]
	v_mov_b32_e32 v196, v200
	v_mov_b32_e32 v197, v201
	ds_read2_b64 v[200:203], v3 offset0:80 offset1:84
	v_add_f32_e32 v123, v236, v123
	v_add_f32_e32 v123, v237, v123
	v_add_f32_e32 v123, v238, v123
	v_add_f32_e32 v103, v239, v123
	v_exp_f32_e32 v121, v121
	v_sub_f32_e32 v123, v206, v102
	s_waitcnt lgkmcnt(1)
	v_mov_b32_e32 v198, v192
	v_mov_b32_e32 v199, v193
	v_sub_f32_e32 v125, v207, v102
	ds_read2_b64 v[204:207], v0 offset0:92 offset1:96
	v_exp_f32_e32 v123, v123
	v_exp_f32_e32 v125, v125
	s_waitcnt lgkmcnt(1)
	v_mfma_f32_16x16x32_bf16 v[180:183], v[200:203], v[188:191], v[180:183]
	ds_read2_b64 v[200:203], v100 offset0:24 offset1:28
	v_add_f32_e32 v103, v121, v103
	v_add_f32_e32 v103, v123, v103
	v_mfma_f32_16x16x32_bf16 v[176:179], v[196:199], v[188:191], v[176:179]
	v_mov_b32_e32 v196, v222
	v_mov_b32_e32 v197, v223
	s_waitcnt lgkmcnt(1)
	v_mov_b32_e32 v198, v204
	v_mov_b32_e32 v199, v205
	v_add_f32_e32 v100, v125, v103
	ds_bpermute_b32 v103, v141, v100
	v_mfma_f32_16x16x32_bf16 v[170:173], v[196:199], v[188:191], v[170:173]
	v_cvt_pk_bf16_f32 v188, v231, v232
	v_cvt_pk_bf16_f32 v189, v233, v234
	v_cvt_pk_bf16_f32 v190, v235, v236
	ds_read2_b64 v[196:199], v1 offset0:36 offset1:40
	v_cvt_pk_bf16_f32 v191, v237, v238
	ds_read2_b64 v[220:223], v0 offset0:100 offset1:104
	s_waitcnt lgkmcnt(2)
	v_add_f32_e32 v100, v100, v103
	v_mfma_f32_16x16x32_bf16 v[130:133], v[200:203], v[188:191], v[130:133]
	ds_read2_b64 v[200:203], v3 offset0:88 offset1:92
	ds_bpermute_b32 v103, v142, v100
	v_fma_f32 v101, v101, s65, -v102
	v_mov_b32_e32 v192, v194
	v_mov_b32_e32 v193, v195
	s_waitcnt lgkmcnt(3)
	v_mov_b32_e32 v194, v196
	v_mov_b32_e32 v195, v197
	v_cvt_pk_bf16_f32 v0, v239, v121
	v_mov_b32_e32 v204, v206
	v_mov_b32_e32 v205, v207
	s_waitcnt lgkmcnt(2)
	v_mov_b32_e32 v206, v220
	v_mov_b32_e32 v207, v221
	v_exp_f32_e32 v121, v101
	v_cvt_pk_bf16_f32 v1, v123, v125
	s_waitcnt lgkmcnt(0)
	v_add_f32_e32 v123, v100, v103
	v_mfma_f32_16x16x32_bf16 v[192:195], v[192:195], v[188:191], v[176:179]
	v_add_f32_e32 v121, v121, v123
	v_mov_b32_e32 v196, v198
	v_mov_b32_e32 v197, v199
	v_mfma_f32_16x16x32_bf16 v[178:181], v[200:203], v[188:191], v[180:183]
	v_mov_b32_e32 v176, v174
	v_mov_b32_e32 v177, v175
	v_mov_b32_e32 v220, v222
	v_mfma_f32_16x16x32_bf16 v[170:173], v[204:207], v[188:191], v[170:173]
	v_mov_b32_e32 v188, v186
	v_mov_b32_e32 v189, v187
	v_mov_b32_e32 v221, v223
	v_div_scale_f32 v123, s[40:41], v121, v121, 1.0
	v_rcp_f32_e32 v125, v123
	v_mov_b32_e32 v3, v2
	v_lshl_add_u64 v[96:97], v[96:97], 0, v[98:99]
	v_lshl_add_u64 v[134:135], s[72:73], 0, v[96:97]
	v_mfma_f32_16x16x32_bf16 v[130:133], v[174:177], v[0:3], v[130:133]
	s_or_b32 s42, s14, 1
	s_cmp_lg_u32 s14, 2
	v_mfma_f32_16x16x32_bf16 v[174:177], v[196:199], v[0:3], v[192:195]
	v_mfma_f32_16x16x32_bf16 v[100:103], v[186:189], v[0:3], v[178:181]
	v_mfma_f32_16x16x32_bf16 v[170:173], v[220:223], v[0:3], v[170:173]
	v_fma_f32 v0, -v123, v125, 1.0
	v_fmac_f32_e32 v125, v0, v125
	v_div_scale_f32 v0, vcc, 1.0, v121, 1.0
	v_mul_f32_e32 v1, v0, v125
	v_fma_f32 v3, -v123, v1, v0
	v_fmac_f32_e32 v1, v3, v125
	v_fma_f32 v0, -v123, v1, v0
	v_div_fmas_f32 v0, v0, v125, v1
	v_div_fixup_f32 v0, v0, v121, 1.0
	v_pk_mul_f32 v[96:97], v[130:131], v[0:1] op_sel_hi:[1,0]
	v_pk_mul_f32 v[98:99], v[132:133], v[0:1] op_sel_hi:[1,0]
	v_cvt_pk_bf16_f32 v96, v96, v97
	v_cvt_pk_bf16_f32 v97, v98, v99
	v_pk_mul_f32 v[98:99], v[174:175], v[0:1] op_sel_hi:[1,0]
	v_pk_mul_f32 v[130:131], v[176:177], v[0:1] op_sel_hi:[1,0]
	v_cvt_pk_bf16_f32 v98, v98, v99
	v_cvt_pk_bf16_f32 v99, v130, v131
	v_add_co_u32_e32 v130, vcc, s74, v134
	v_mov_b32_e32 v3, v113
	s_nop 0
	v_addc_co_u32_e32 v131, vcc, 0, v135, vcc
	global_store_dwordx4 v[130:131], v[96:99], off offset:1024 nt
	s_nop 1
	v_pk_mul_f32 v[96:97], v[100:101], v[0:1] op_sel_hi:[1,0]
	v_pk_mul_f32 v[98:99], v[102:103], v[0:1] op_sel_hi:[1,0]
	v_cvt_pk_bf16_f32 v96, v96, v97
	v_cvt_pk_bf16_f32 v97, v98, v99
	v_pk_mul_f32 v[98:99], v[170:171], v[0:1] op_sel_hi:[1,0]
	v_pk_mul_f32 v[0:1], v[172:173], v[0:1] op_sel_hi:[1,0]
	v_cvt_pk_bf16_f32 v98, v98, v99
	v_cvt_pk_bf16_f32 v99, v0, v1
	v_mov_b32_e32 v0, v112
	global_store_dwordx4 v[130:131], v[96:99], off offset:1088 nt
	s_nop 0
	v_ashrrev_i32_e32 v1, 31, v0
	v_lshlrev_b32_e32 v130, 3, v3
	v_ashrrev_i32_e32 v131, 31, v130
	v_lshl_add_u64 v[132:133], v[126:127], 0, v[0:1]
	s_cbranch_scc0 .LBB0_431
	s_or_b32 s40, s42, s15
	v_lshlrev_b64 v[96:97], 1, v[130:131]
	s_lshl_b32 s94, s40, 6
	v_mad_u64_u32 v[96:97], s[40:41], v132, s62, v[96:97]
	v_mov_b32_e32 v98, v97
	v_mad_u64_u32 v[98:99], s[40:41], v133, s62, v[98:99]
	s_add_u32 s40, s12, s70
	v_mov_b32_e32 v97, v98
	s_addc_u32 s41, s13, s71
	v_lshl_add_u64 v[96:97], s[40:41], 0, v[96:97]
	v_add_co_u32_e32 v100, vcc, 0xbe00000, v96
	s_nop 1
	v_addc_co_u32_e32 v101, vcc, 0, v97, vcc
	global_load_dwordx4 v[96:99], v[100:101], off offset:3328
	s_nop 0
	global_load_dwordx4 v[100:103], v[100:101], off offset:3392
	v_mov_b64_e32 v[134:135], s[94:95]
	s_mov_b32 s57, 0x42fc0000
	s_cbranch_execnz .LBB0_428
	s_branch .LBB0_427

.LBB0_521:
	s_waitcnt vmcnt(19) lgkmcnt(1)
	v_mfma_f32_16x16x32_bf16 v[92:95], v[92:95], v[104:107], v[140:143]
	v_ashrrev_i32_e32 v207, 31, v206
	v_mov_b32_e32 v205, v2
	v_mov_b32_e32 v183, v2
	s_waitcnt vmcnt(17)
	v_mfma_f32_16x16x32_bf16 v[96:99], v[96:99], v[104:107], v[144:147]
	v_readlane_b32 s16, v254, 40
	s_waitcnt vmcnt(15)
	v_mfma_f32_16x16x32_bf16 v[76:79], v[76:79], v[104:107], v[132:135]
	v_add_u32_e32 v247, s16, v247
	v_readlane_b32 s16, v254, 42
	s_waitcnt lgkmcnt(0)
	v_mfma_f32_16x16x32_bf16 v[88:91], v[88:91], v[100:103], v[92:95]
	v_add_u32_e32 v248, s16, v248
	v_readlane_b32 s16, v254, 44
	v_mfma_f32_16x16x32_bf16 v[84:87], v[84:87], v[100:103], v[96:99]
	s_nop 0
	v_add_u32_e32 v157, s16, v157
	s_nop 2
	v_mov_b32_e32 v92, v89
	v_mov_b32_e32 v0, v88
	s_waitcnt vmcnt(11)
	v_mfma_f32_16x16x32_bf16 v[64:67], v[64:67], v[104:107], v[112:115]
	v_mov_b32_e32 v94, v91
	v_mov_b32_e32 v93, v85
	v_mov_b32_e32 v1, v84
	v_mfma_f32_16x16x32_bf16 v[68:71], v[68:71], v[100:103], v[76:79]
	v_mul_f32_e64 v92, v92, v92
	v_mul_f32_e64 v93, v93, v93
	v_mov_b32_e32 v95, v87
	v_pk_fma_f32 v[0:1], v[0:1], v[0:1], v[92:93]
	s_waitcnt vmcnt(9)
	v_mfma_f32_16x16x32_bf16 v[76:79], v[80:83], v[104:107], v[136:139]
	v_mov_b32_e32 v92, v90
	v_mov_b32_e32 v93, v86
	v_pk_mul_f32 v[94:95], v[94:95], v[94:95]
	s_waitcnt vmcnt(7)
	v_mfma_f32_16x16x32_bf16 v[56:59], v[56:59], v[104:107], v[116:119]
	v_fma_f32 v92, v92, v92, v94
	v_fma_f32 v93, v93, v93, v95
	v_pk_mul_f32 v[94:95], v[68:69], v[68:69]
	v_pk_add_f32 v[0:1], v[0:1], v[92:93]
	v_mfma_f32_16x16x32_bf16 v[52:55], v[52:55], v[100:103], v[64:67]
	v_mul_f32_e64 v92, v70, v70
	v_mul_f32_e64 v93, v71, v71
	v_pk_add_f32 v[0:1], v[0:1], v[0:1] op_sel:[0,1] op_sel_hi:[1,0]
	v_pk_mov_b32 v[80:81], v[94:95], v[92:93] op_sel:[1,0]
	v_mfma_f32_16x16x32_bf16 v[72:75], v[72:75], v[100:103], v[76:79]
	v_mov_b32_e32 v95, v93
	v_pk_add_f32 v[80:81], v[80:81], v[94:95]
	s_nop 0
	v_mul_f32_e32 v64, v53, v53
	s_waitcnt vmcnt(5)
	v_mfma_f32_16x16x32_bf16 v[40:43], v[40:43], v[104:107], v[108:111]
	v_mul_f32_e32 v66, v55, v55
	s_nop 0
	v_mul_f32_e32 v3, v72, v72
	v_mul_f32_e32 v78, v73, v73
	v_mfma_f32_16x16x32_bf16 v[44:47], v[44:47], v[100:103], v[56:59]
	v_mul_f32_e32 v79, v74, v74
	v_mul_f32_e32 v82, v75, v75
	v_pk_add_f32 v[76:77], v[80:81], v[80:81] op_sel:[0,1] op_sel_hi:[1,0]
	s_waitcnt vmcnt(1)
	v_mfma_f32_16x16x32_bf16 v[56:59], v[60:63], v[104:107], v[120:123]
	v_pk_fma_f32 v[64:65], v[52:53], v[52:53], v[64:65] op_sel_hi:[1,1,0]
	v_pk_fma_f32 v[66:67], v[54:55], v[54:55], v[66:67] op_sel_hi:[1,1,0]
	v_mov_b32_e32 v1, v3
	v_mov_b32_e32 v77, v78
	v_mov_b32_e32 v65, v79
	v_mov_b32_e32 v67, v82
	v_mfma_f32_16x16x32_bf16 v[36:39], v[36:39], v[100:103], v[40:43]
	v_add_f32_e64 v0, v0, v76
	v_add_f32_e64 v1, v1, v77
	v_pk_add_f32 v[64:65], v[64:65], v[66:67]
	v_pk_mul_f32 v[66:67], v[44:45], v[44:45]
	s_waitcnt vmcnt(0)
	v_mfma_f32_16x16x32_bf16 v[48:51], v[48:51], v[100:103], v[56:59]
	v_add_f32_e64 v0, v0, v64
	v_add_f32_e64 v1, v1, v65
	v_pk_mul_f32 v[64:65], v[46:47], v[46:47]
	v_mul_f32_e32 v40, v37, v37
	v_pk_mov_b32 v[60:61], v[66:67], v[64:65] op_sel:[1,0]
	v_mov_b32_e32 v67, v65
	v_pk_add_f32 v[60:61], v[60:61], v[66:67]
	v_mul_f32_e32 v42, v39, v39
	v_mul_f32_e32 v3, v48, v48
	v_mul_f32_e32 v58, v49, v49
	v_mul_f32_e32 v59, v50, v50
	v_mul_f32_e32 v62, v51, v51
	v_pk_add_f32 v[0:1], v[0:1], v[0:1] op_sel:[0,1] op_sel_hi:[1,0]
	v_pk_add_f32 v[56:57], v[60:61], v[60:61] op_sel:[0,1] op_sel_hi:[1,0]
	v_pk_fma_f32 v[40:41], v[36:37], v[36:37], v[40:41] op_sel_hi:[1,1,0]
	v_pk_fma_f32 v[42:43], v[38:39], v[38:39], v[42:43] op_sel_hi:[1,1,0]
	v_mov_b32_e32 v1, v3
	v_mov_b32_e32 v57, v58
	v_mov_b32_e32 v41, v59
	v_mov_b32_e32 v43, v62
	v_pk_add_f32 v[0:1], v[0:1], v[56:57]
	v_pk_add_f32 v[40:41], v[40:41], v[42:43]
	s_nop 0
	v_pk_add_f32 v[0:1], v[0:1], v[40:41]
	v_lshlrev_b64 v[40:41], 11, v[206:207]
	v_add_f32_e32 v0, v0, v1
	ds_bpermute_b32 v1, v237, v0
	v_lshl_add_u64 v[56:57], s[22:23], 0, v[40:41]
	ds_read_b128 v[40:43], v243
	v_lshl_add_u64 v[60:61], v[56:57], 0, v[204:205]
	ds_read_b128 v[56:59], v243 offset:16
	s_waitcnt lgkmcnt(2)
	v_add_f32_e32 v0, v0, v1
	ds_bpermute_b32 v1, v238, v0
	s_waitcnt lgkmcnt(0)
	v_add_f32_e32 v0, v0, v1
	v_fmamk_f32 v0, v0, 0x3c000000, v209
	v_mul_f32_e32 v1, 0x4b800000, v0
	v_cmp_gt_f32_e32 vcc, s68, v0
	s_nop 1
	v_cndmask_b32_e32 v0, v0, v1, vcc
	v_rsq_f32_e32 v0, v0
	s_nop 0
	v_mul_f32_e32 v1, 0x45800000, v0
	v_cndmask_b32_e32 v0, v0, v1, vcc
	v_pk_mul_f32 v[62:63], v[88:89], v[0:1] op_sel_hi:[1,0]
	s_andn2_b64 vcc, exec, s[54:55]
	v_pk_mul_f32 v[40:41], v[40:41], v[62:63]
	v_lshlrev_b32_e32 v62, 16, v32
	v_and_b32_e32 v63, 0xffff0000, v32
	v_pk_mul_f32 v[40:41], v[40:41], v[62:63]
	s_nop 0
	v_cvt_pk_bf16_f32 v32, v40, v41
	v_pk_mul_f32 v[40:41], v[90:91], v[0:1] op_sel_hi:[1,0]
	s_nop 0
	v_pk_mul_f32 v[40:41], v[42:43], v[40:41]
	v_lshlrev_b32_e32 v42, 16, v33
	v_and_b32_e32 v43, 0xffff0000, v33
	v_pk_mul_f32 v[40:41], v[40:41], v[42:43]
	v_lshlrev_b32_e32 v42, 16, v34
	v_cvt_pk_bf16_f32 v33, v40, v41
	v_pk_mul_f32 v[40:41], v[84:85], v[0:1] op_sel_hi:[1,0]
	v_and_b32_e32 v43, 0xffff0000, v34
	v_pk_mul_f32 v[40:41], v[56:57], v[40:41]
	v_lshl_add_u64 v[56:57], v[60:61], 0, v[182:183]
	v_pk_mul_f32 v[40:41], v[40:41], v[42:43]
	v_lshlrev_b32_e32 v42, 16, v35
	v_cvt_pk_bf16_f32 v34, v40, v41
	v_pk_mul_f32 v[40:41], v[86:87], v[0:1] op_sel_hi:[1,0]
	v_and_b32_e32 v43, 0xffff0000, v35
	v_pk_mul_f32 v[40:41], v[58:59], v[40:41]
	v_pk_mul_f32 v[58:59], v[68:69], v[0:1] op_sel_hi:[1,0]
	v_pk_mul_f32 v[40:41], v[40:41], v[42:43]
	s_nop 0
	v_cvt_pk_bf16_f32 v35, v40, v41
	ds_read_b128 v[40:43], v244
	global_store_dwordx4 v[56:57], v[32:35], off nt
	ds_read_b128 v[32:35], v244 offset:16
	s_waitcnt lgkmcnt(1)
	v_pk_mul_f32 v[40:41], v[40:41], v[58:59]
	v_lshlrev_b32_e32 v58, 16, v28
	v_and_b32_e32 v59, 0xffff0000, v28
	v_pk_mul_f32 v[40:41], v[40:41], v[58:59]
	s_nop 0
	v_cvt_pk_bf16_f32 v28, v40, v41
	v_pk_mul_f32 v[40:41], v[70:71], v[0:1] op_sel_hi:[1,0]
	s_nop 0
	v_pk_mul_f32 v[40:41], v[42:43], v[40:41]
	v_lshlrev_b32_e32 v42, 16, v29
	v_and_b32_e32 v43, 0xffff0000, v29
	v_pk_mul_f32 v[40:41], v[40:41], v[42:43]
	s_nop 0
	v_cvt_pk_bf16_f32 v29, v40, v41
	v_pk_mul_f32 v[40:41], v[52:53], v[0:1] op_sel_hi:[1,0]
	s_waitcnt lgkmcnt(0)
	v_pk_mul_f32 v[32:33], v[32:33], v[40:41]
	v_lshlrev_b32_e32 v40, 16, v30
	v_and_b32_e32 v41, 0xffff0000, v30
	v_pk_mul_f32 v[32:33], v[32:33], v[40:41]
	s_nop 0
	v_cvt_pk_bf16_f32 v30, v32, v33
	v_pk_mul_f32 v[32:33], v[54:55], v[0:1] op_sel_hi:[1,0]
	s_nop 0
	v_pk_mul_f32 v[32:33], v[34:35], v[32:33]
	v_lshlrev_b32_e32 v34, 16, v31
	v_and_b32_e32 v35, 0xffff0000, v31
	v_pk_mul_f32 v[40:41], v[32:33], v[34:35]
	ds_read_b128 v[32:35], v245
	v_cvt_pk_bf16_f32 v31, v40, v41
	v_pk_mul_f32 v[40:41], v[72:73], v[0:1] op_sel_hi:[1,0]
	global_store_dwordx4 v[56:57], v[28:31], off offset:64 nt
	ds_read_b128 v[28:31], v245 offset:16
	s_waitcnt lgkmcnt(1)
	v_pk_mul_f32 v[32:33], v[32:33], v[40:41]
	v_lshlrev_b32_e32 v40, 16, v24
	v_and_b32_e32 v41, 0xffff0000, v24
	v_pk_mul_f32 v[32:33], v[32:33], v[40:41]
	s_nop 0
	v_cvt_pk_bf16_f32 v24, v32, v33
	v_pk_mul_f32 v[32:33], v[74:75], v[0:1] op_sel_hi:[1,0]
	s_nop 0
	v_pk_mul_f32 v[32:33], v[34:35], v[32:33]
	v_lshlrev_b32_e32 v34, 16, v25
	v_and_b32_e32 v35, 0xffff0000, v25
	v_pk_mul_f32 v[32:33], v[32:33], v[34:35]
	s_nop 0
	v_cvt_pk_bf16_f32 v25, v32, v33
	v_pk_mul_f32 v[32:33], v[44:45], v[0:1] op_sel_hi:[1,0]
	s_waitcnt lgkmcnt(0)
	v_pk_mul_f32 v[28:29], v[28:29], v[32:33]
	v_lshlrev_b32_e32 v32, 16, v26
	v_and_b32_e32 v33, 0xffff0000, v26
	v_pk_mul_f32 v[28:29], v[28:29], v[32:33]
	s_nop 0
	v_cvt_pk_bf16_f32 v26, v28, v29
	v_pk_mul_f32 v[28:29], v[46:47], v[0:1] op_sel_hi:[1,0]
	s_nop 0
	v_pk_mul_f32 v[28:29], v[30:31], v[28:29]
	v_lshlrev_b32_e32 v30, 16, v27
	v_and_b32_e32 v31, 0xffff0000, v27
	v_pk_mul_f32 v[32:33], v[28:29], v[30:31]
	ds_read_b128 v[28:31], v246
	v_cvt_pk_bf16_f32 v27, v32, v33
	v_pk_mul_f32 v[32:33], v[36:37], v[0:1] op_sel_hi:[1,0]
	global_store_dwordx4 v[56:57], v[24:27], off offset:128 nt
	ds_read_b128 v[24:27], v246 offset:16
	s_waitcnt lgkmcnt(1)
	v_pk_mul_f32 v[28:29], v[28:29], v[32:33]
	v_lshlrev_b32_e32 v32, 16, v20
	v_and_b32_e32 v33, 0xffff0000, v20
	v_pk_mul_f32 v[28:29], v[28:29], v[32:33]
	s_nop 0
	v_cvt_pk_bf16_f32 v20, v28, v29
	v_pk_mul_f32 v[28:29], v[38:39], v[0:1] op_sel_hi:[1,0]
	s_nop 0
	v_pk_mul_f32 v[28:29], v[30:31], v[28:29]
	v_lshlrev_b32_e32 v30, 16, v21
	v_and_b32_e32 v31, 0xffff0000, v21
	v_pk_mul_f32 v[28:29], v[28:29], v[30:31]
	s_nop 0
	v_cvt_pk_bf16_f32 v21, v28, v29
	v_pk_mul_f32 v[28:29], v[48:49], v[0:1] op_sel_hi:[1,0]
	v_pk_mul_f32 v[0:1], v[50:51], v[0:1] op_sel_hi:[1,0]
	s_waitcnt lgkmcnt(0)
	v_pk_mul_f32 v[24:25], v[24:25], v[28:29]
	v_lshlrev_b32_e32 v28, 16, v22
	v_and_b32_e32 v29, 0xffff0000, v22
	v_pk_mul_f32 v[24:25], v[24:25], v[28:29]
	v_pk_mul_f32 v[0:1], v[26:27], v[0:1]
	v_cvt_pk_bf16_f32 v22, v24, v25
	v_lshlrev_b32_e32 v24, 16, v23
	v_and_b32_e32 v25, 0xffff0000, v23
	v_pk_mul_f32 v[0:1], v[0:1], v[24:25]
	s_nop 0
	v_cvt_pk_bf16_f32 v23, v0, v1
	global_store_dwordx4 v[56:57], v[20:23], off offset:192 nt
	s_barrier
	s_cbranch_vccz .LBB0_553

.Lup_nohp110:
	v_pk_mul_f32 v[150:151], v[96:97], s[10:11]
	v_pk_mul_f32 v[152:153], v[98:99], s[10:11]
	v_pk_mul_f32 v[158:159], v[92:93], s[10:11]
	v_pk_mul_f32 v[160:161], v[94:95], s[10:11]
	v_exp_f32_e32 v150, v150
	v_exp_f32_e32 v151, v151
	v_exp_f32_e32 v152, v152
	v_exp_f32_e32 v153, v153
	v_exp_f32_e32 v158, v158
	v_exp_f32_e32 v159, v159
	v_exp_f32_e32 v160, v160
	v_exp_f32_e32 v161, v161
	v_pk_add_f32 v[150:151], v[150:151], s[12:13]
	v_pk_add_f32 v[152:153], v[152:153], s[12:13]
	v_pk_add_f32 v[158:159], v[158:159], s[12:13]
	v_pk_add_f32 v[160:161], v[160:161], s[12:13]
	v_rcp_f32_e32 v150, v150
	v_rcp_f32_e32 v151, v151
	v_rcp_f32_e32 v152, v152
	v_rcp_f32_e32 v153, v153
	v_rcp_f32_e32 v158, v158
	v_rcp_f32_e32 v159, v159
	v_rcp_f32_e32 v160, v160
	v_rcp_f32_e32 v161, v161
	v_pk_mul_f32 v[150:151], v[96:97], v[150:151]
	v_pk_mul_f32 v[152:153], v[98:99], v[152:153]
	v_pk_mul_f32 v[158:159], v[92:93], v[158:159]
	v_pk_mul_f32 v[160:161], v[94:95], v[160:161]
	v_pk_mul_f32 v[150:151], v[150:151], v[80:81]
	v_pk_mul_f32 v[152:153], v[152:153], v[82:83]
	v_pk_mul_f32 v[158:159], v[158:159], v[76:77]
	v_pk_mul_f32 v[160:161], v[160:161], v[78:79]
	v_cvt_pk_bf16_f32 v130, v150, v151
	v_cvt_pk_bf16_f32 v131, v152, v153
	v_cvt_pk_bf16_f32 v126, v158, v159
	v_cvt_pk_bf16_f32 v127, v160, v161
	v_pk_mul_f32 v[150:151], v[88:89], s[10:11]
	v_pk_mul_f32 v[152:153], v[90:91], s[10:11]
	v_pk_mul_f32 v[158:159], v[84:85], s[10:11]
	v_pk_mul_f32 v[160:161], v[86:87], s[10:11]
	v_exp_f32_e32 v150, v150
	v_exp_f32_e32 v151, v151
	v_exp_f32_e32 v152, v152
	v_exp_f32_e32 v153, v153
	v_exp_f32_e32 v158, v158
	v_exp_f32_e32 v159, v159
	v_exp_f32_e32 v160, v160
	v_exp_f32_e32 v161, v161
	v_pk_add_f32 v[150:151], v[150:151], s[12:13]
	v_pk_add_f32 v[152:153], v[152:153], s[12:13]
	v_pk_add_f32 v[158:159], v[158:159], s[12:13]
	v_pk_add_f32 v[160:161], v[160:161], s[12:13]
	v_rcp_f32_e32 v150, v150
	v_rcp_f32_e32 v151, v151
	v_rcp_f32_e32 v152, v152
	v_rcp_f32_e32 v153, v153
	v_rcp_f32_e32 v158, v158
	v_rcp_f32_e32 v159, v159
	v_rcp_f32_e32 v160, v160
	v_rcp_f32_e32 v161, v161
	v_pk_mul_f32 v[150:151], v[88:89], v[150:151]
	v_pk_mul_f32 v[152:153], v[90:91], v[152:153]
	v_pk_mul_f32 v[158:159], v[84:85], v[158:159]
	v_pk_mul_f32 v[160:161], v[86:87], v[160:161]
	v_pk_mul_f32 v[150:151], v[150:151], v[72:73]
	v_pk_mul_f32 v[152:153], v[152:153], v[74:75]
	v_pk_mul_f32 v[158:159], v[158:159], v[68:69]
	v_pk_mul_f32 v[160:161], v[160:161], v[70:71]
	v_cvt_pk_bf16_f32 v122, v150, v151
	v_cvt_pk_bf16_f32 v123, v152, v153
	v_cvt_pk_bf16_f32 v118, v158, v159
	v_cvt_pk_bf16_f32 v119, v160, v161
	global_store_dwordx4 v221, v[128:131], s[14:15] offset:0 nt
	global_store_dwordx4 v221, v[124:127], s[14:15] offset:128 nt
	global_store_dwordx4 v221, v[120:123], s[14:15] offset:256 nt
	global_store_dwordx4 v221, v[116:119], s[14:15] offset:384 nt
	s_waitcnt lgkmcnt(0)
	v_mov_b32_dpp v234, v4 row_shr:1 row_mask:0xf bank_mask:0xf
	v_mov_b32_dpp v235, v5 row_shr:1 row_mask:0xf bank_mask:0xf
	v_mov_b32_dpp v236, v6 row_shr:1 row_mask:0xf bank_mask:0xf
	v_mov_b32_dpp v237, v7 row_shr:1 row_mask:0xf bank_mask:0xf
	v_mov_b32_dpp v230, v8 row_shr:1 row_mask:0xf bank_mask:0xf
	v_mov_b32_dpp v231, v9 row_shr:1 row_mask:0xf bank_mask:0xf
	v_mov_b32_dpp v232, v10 row_shr:1 row_mask:0xf bank_mask:0xf
	v_mov_b32_dpp v233, v11 row_shr:1 row_mask:0xf bank_mask:0xf
	s_and_b64 vcc, exec, s[28:29]
	s_cbranch_vccz .Lup_nohc111
	v_pk_mul_f32 v[200:201], v[184:185], v[4:5]
	v_pk_mul_f32 v[202:203], v[186:187], v[6:7]
	v_pk_mul_f32 v[238:239], v[184:185], v[8:9]
	v_pk_mul_f32 v[240:241], v[186:187], v[10:11]
	v_pk_fma_f32 v[238:239], v[188:189], v[4:5], v[238:239]
	v_pk_fma_f32 v[240:241], v[190:191], v[6:7], v[240:241]
	s_add_u32 s48, s24, s41
	s_addc_u32 s49, s25, 0
	s_add_u32 s16, s48, 0x5800
	s_addc_u32 s17, s49, 0
	s_and_saveexec_b64 s[52:53], s[56:57]
	global_store_dwordx4 v3, v[200:203], s[48:49] offset:528
	global_store_dwordx4 v3, v[238:241], s[16:17] offset:528
	s_mov_b64 exec, s[52:53]
.Lup_nohc111:
	v_pk_fma_f32 v[4:5], v[4:5], v[192:193], v[196:197]
	v_pk_fma_f32 v[6:7], v[6:7], v[194:195], v[198:199]
	v_pk_fma_f32 v[4:5], v[8:9], v[188:189], v[4:5]
	v_pk_fma_f32 v[6:7], v[10:11], v[190:191], v[6:7]
	v_pk_fma_f32 v[4:5], v[12:13], v[184:185], v[4:5]
	v_pk_fma_f32 v[6:7], v[14:15], v[186:187], v[6:7]
	v_pk_fma_f32 v[8:9], v[8:9], v[192:193], v[196:197]
	v_pk_fma_f32 v[10:11], v[10:11], v[194:195], v[198:199]
	v_pk_fma_f32 v[8:9], v[12:13], v[188:189], v[8:9]
	v_pk_fma_f32 v[10:11], v[14:15], v[190:191], v[10:11]
	v_pk_fma_f32 v[8:9], v[16:17], v[184:185], v[8:9]
	v_pk_fma_f32 v[10:11], v[18:19], v[186:187], v[10:11]
	v_pk_fma_f32 v[12:13], v[12:13], v[192:193], v[196:197]
	v_pk_fma_f32 v[14:15], v[14:15], v[194:195], v[198:199]
	v_pk_fma_f32 v[12:13], v[16:17], v[188:189], v[12:13]
	v_pk_fma_f32 v[14:15], v[18:19], v[190:191], v[14:15]
	v_pk_fma_f32 v[12:13], v[234:235], v[184:185], v[12:13]
	v_pk_fma_f32 v[14:15], v[236:237], v[186:187], v[14:15]
	v_pk_fma_f32 v[16:17], v[16:17], v[192:193], v[196:197]
	v_pk_fma_f32 v[18:19], v[18:19], v[194:195], v[198:199]
	v_pk_fma_f32 v[16:17], v[234:235], v[188:189], v[16:17]
	v_pk_fma_f32 v[18:19], v[236:237], v[190:191], v[18:19]
	v_pk_fma_f32 v[16:17], v[230:231], v[184:185], v[16:17]
	v_pk_fma_f32 v[18:19], v[232:233], v[186:187], v[18:19]
	v_pk_mul_f32 v[150:151], v[32:33], s[10:11]
	v_pk_mul_f32 v[152:153], v[34:35], s[10:11]
	v_pk_mul_f32 v[158:159], v[28:29], s[10:11]
	v_pk_mul_f32 v[160:161], v[30:31], s[10:11]
	v_exp_f32_e32 v150, v150
	v_exp_f32_e32 v151, v151
	v_exp_f32_e32 v152, v152
	v_exp_f32_e32 v153, v153
	v_exp_f32_e32 v158, v158
	v_exp_f32_e32 v159, v159
	v_exp_f32_e32 v160, v160
	v_exp_f32_e32 v161, v161
	v_pk_add_f32 v[150:151], v[150:151], s[12:13]
	v_pk_add_f32 v[152:153], v[152:153], s[12:13]
	v_pk_add_f32 v[158:159], v[158:159], s[12:13]
	v_pk_add_f32 v[160:161], v[160:161], s[12:13]
	v_rcp_f32_e32 v150, v150
	v_rcp_f32_e32 v151, v151
	v_rcp_f32_e32 v152, v152
	v_rcp_f32_e32 v153, v153
	v_rcp_f32_e32 v158, v158
	v_rcp_f32_e32 v159, v159
	v_rcp_f32_e32 v160, v160
	v_rcp_f32_e32 v161, v161
	v_pk_mul_f32 v[150:151], v[32:33], v[150:151]
	v_pk_mul_f32 v[152:153], v[34:35], v[152:153]
	v_pk_mul_f32 v[158:159], v[28:29], v[158:159]
	v_pk_mul_f32 v[160:161], v[30:31], v[160:161]
	v_pk_mul_f32 v[150:151], v[150:151], v[16:17]
	v_pk_mul_f32 v[152:153], v[152:153], v[18:19]
	v_pk_mul_f32 v[158:159], v[158:159], v[12:13]
	v_pk_mul_f32 v[160:161], v[160:161], v[14:15]
	v_cvt_pk_bf16_f32 v66, v150, v151
	v_cvt_pk_bf16_f32 v67, v152, v153
	v_cvt_pk_bf16_f32 v62, v158, v159
	v_cvt_pk_bf16_f32 v63, v160, v161
	v_pk_mul_f32 v[150:151], v[24:25], s[10:11]
	v_pk_mul_f32 v[152:153], v[26:27], s[10:11]
	v_pk_mul_f32 v[158:159], v[20:21], s[10:11]
	v_pk_mul_f32 v[160:161], v[22:23], s[10:11]
	v_exp_f32_e32 v150, v150
	v_exp_f32_e32 v151, v151
	v_exp_f32_e32 v152, v152
	v_exp_f32_e32 v153, v153
	v_exp_f32_e32 v158, v158
	v_exp_f32_e32 v159, v159
	v_exp_f32_e32 v160, v160
	v_exp_f32_e32 v161, v161
	v_pk_add_f32 v[150:151], v[150:151], s[12:13]
	v_pk_add_f32 v[152:153], v[152:153], s[12:13]
	v_pk_add_f32 v[158:159], v[158:159], s[12:13]
	v_pk_add_f32 v[160:161], v[160:161], s[12:13]
	v_rcp_f32_e32 v150, v150
	v_rcp_f32_e32 v151, v151
	v_rcp_f32_e32 v152, v152
	v_rcp_f32_e32 v153, v153
	v_rcp_f32_e32 v158, v158
	v_rcp_f32_e32 v159, v159
	v_rcp_f32_e32 v160, v160
	v_rcp_f32_e32 v161, v161
	v_pk_mul_f32 v[150:151], v[24:25], v[150:151]
	v_pk_mul_f32 v[152:153], v[26:27], v[152:153]
	v_pk_mul_f32 v[158:159], v[20:21], v[158:159]
	v_pk_mul_f32 v[160:161], v[22:23], v[160:161]
	v_pk_mul_f32 v[150:151], v[150:151], v[8:9]
	v_pk_mul_f32 v[152:153], v[152:153], v[10:11]
	v_pk_mul_f32 v[158:159], v[158:159], v[4:5]
	v_pk_mul_f32 v[160:161], v[160:161], v[6:7]
	v_cvt_pk_bf16_f32 v58, v150, v151
	v_cvt_pk_bf16_f32 v59, v152, v153
	v_cvt_pk_bf16_f32 v54, v158, v159
	v_cvt_pk_bf16_f32 v55, v160, v161
	global_store_dwordx4 v221, v[64:67], s[50:51] offset:0 nt
	global_store_dwordx4 v221, v[60:63], s[50:51] offset:128 nt
	global_store_dwordx4 v221, v[56:59], s[50:51] offset:256 nt
	global_store_dwordx4 v221, v[52:55], s[50:51] offset:384 nt
	s_mov_b64 s[10:11], -1
	s_andn2_b64 vcc, exec, s[8:9]
	s_cbranch_vccnz .LBB0_675
	v_readlane_b32 s8, v253, 13
	v_readlane_b32 s9, v253, 14
	s_andn2_b64 vcc, exec, s[8:9]
	s_cbranch_vccnz .LBB0_674
	s_barrier
	s_branch .LBB0_674

.Lres7a_nobar:
	s_waitcnt vmcnt(15)
	v_lshlrev_b32_e32 v147, 16, v170
	v_and_b32_e32 v170, 0xffff0000, v170
	v_add_f32_e32 v128, v128, v147
	v_add_f32_e32 v129, v129, v170
	v_lshlrev_b32_e32 v147, 16, v171
	v_and_b32_e32 v171, 0xffff0000, v171
	v_add_f32_e32 v130, v130, v147
	v_add_f32_e32 v131, v131, v171
	v_lshlrev_b32_e32 v147, 16, v172
	v_and_b32_e32 v172, 0xffff0000, v172
	v_add_f32_e32 v124, v124, v147
	v_add_f32_e32 v125, v125, v172
	v_lshlrev_b32_e32 v147, 16, v173
	v_and_b32_e32 v173, 0xffff0000, v173
	v_add_f32_e32 v126, v126, v147
	v_add_f32_e32 v127, v127, v173
	s_waitcnt vmcnt(14)
	v_lshlrev_b32_e32 v147, 16, v174
	v_and_b32_e32 v174, 0xffff0000, v174
	v_add_f32_e32 v120, v120, v147
	v_add_f32_e32 v121, v121, v174
	v_lshlrev_b32_e32 v147, 16, v175
	v_and_b32_e32 v175, 0xffff0000, v175
	v_add_f32_e32 v122, v122, v147
	v_add_f32_e32 v123, v123, v175
	v_lshlrev_b32_e32 v147, 16, v176
	v_and_b32_e32 v176, 0xffff0000, v176
	v_add_f32_e32 v116, v116, v147
	v_add_f32_e32 v117, v117, v176
	v_lshlrev_b32_e32 v147, 16, v177
	v_and_b32_e32 v177, 0xffff0000, v177
	v_add_f32_e32 v118, v118, v147
	v_add_f32_e32 v119, v119, v177
	s_waitcnt vmcnt(13)
	v_lshlrev_b32_e32 v147, 16, v178
	v_and_b32_e32 v178, 0xffff0000, v178
	v_add_f32_e32 v112, v112, v147
	v_add_f32_e32 v113, v113, v178
	v_lshlrev_b32_e32 v147, 16, v179
	v_and_b32_e32 v179, 0xffff0000, v179
	v_add_f32_e32 v114, v114, v147
	v_add_f32_e32 v115, v115, v179
	v_lshlrev_b32_e32 v147, 16, v180
	v_and_b32_e32 v180, 0xffff0000, v180
	v_add_f32_e32 v108, v108, v147
	v_add_f32_e32 v109, v109, v180
	v_lshlrev_b32_e32 v147, 16, v181
	v_and_b32_e32 v181, 0xffff0000, v181
	v_add_f32_e32 v110, v110, v147
	v_add_f32_e32 v111, v111, v181
	s_waitcnt vmcnt(12)
	v_lshlrev_b32_e32 v147, 16, v182
	v_and_b32_e32 v182, 0xffff0000, v182
	v_add_f32_e32 v104, v104, v147
	v_add_f32_e32 v105, v105, v182
	v_lshlrev_b32_e32 v147, 16, v183
	v_and_b32_e32 v183, 0xffff0000, v183
	v_add_f32_e32 v106, v106, v147
	v_add_f32_e32 v107, v107, v183
	v_lshlrev_b32_e32 v147, 16, v184
	v_and_b32_e32 v184, 0xffff0000, v184
	v_add_f32_e32 v100, v100, v147
	v_add_f32_e32 v101, v101, v184
	v_lshlrev_b32_e32 v147, 16, v185
	v_and_b32_e32 v185, 0xffff0000, v185
	v_add_f32_e32 v102, v102, v147
	v_add_f32_e32 v103, v103, v185
	s_waitcnt vmcnt(11)
	v_lshlrev_b32_e32 v147, 16, v186
	v_and_b32_e32 v186, 0xffff0000, v186
	v_add_f32_e32 v96, v96, v147
	v_add_f32_e32 v97, v97, v186
	v_lshlrev_b32_e32 v147, 16, v187
	v_and_b32_e32 v187, 0xffff0000, v187
	v_add_f32_e32 v98, v98, v147
	v_add_f32_e32 v99, v99, v187
	v_lshlrev_b32_e32 v147, 16, v188
	v_and_b32_e32 v188, 0xffff0000, v188
	v_add_f32_e32 v92, v92, v147
	v_add_f32_e32 v93, v93, v188
	v_lshlrev_b32_e32 v147, 16, v189
	v_and_b32_e32 v189, 0xffff0000, v189
	v_add_f32_e32 v94, v94, v147
	v_add_f32_e32 v95, v95, v189
	s_waitcnt vmcnt(10)
	v_lshlrev_b32_e32 v147, 16, v190
	v_and_b32_e32 v190, 0xffff0000, v190
	v_add_f32_e32 v88, v88, v147
	v_add_f32_e32 v89, v89, v190
	v_lshlrev_b32_e32 v147, 16, v191
	v_and_b32_e32 v191, 0xffff0000, v191
	v_add_f32_e32 v90, v90, v147
	v_add_f32_e32 v91, v91, v191
	v_lshlrev_b32_e32 v147, 16, v192
	v_and_b32_e32 v192, 0xffff0000, v192
	v_add_f32_e32 v84, v84, v147
	v_add_f32_e32 v85, v85, v192
	v_lshlrev_b32_e32 v147, 16, v193
	v_and_b32_e32 v193, 0xffff0000, v193
	v_add_f32_e32 v86, v86, v147
	v_add_f32_e32 v87, v87, v193
	s_waitcnt vmcnt(9)
	v_lshlrev_b32_e32 v147, 16, v194
	v_and_b32_e32 v194, 0xffff0000, v194
	v_add_f32_e32 v80, v80, v147
	v_add_f32_e32 v81, v81, v194
	v_lshlrev_b32_e32 v147, 16, v195
	v_and_b32_e32 v195, 0xffff0000, v195
	v_add_f32_e32 v82, v82, v147
	v_add_f32_e32 v83, v83, v195
	v_lshlrev_b32_e32 v147, 16, v196
	v_and_b32_e32 v196, 0xffff0000, v196
	v_add_f32_e32 v76, v76, v147
	v_add_f32_e32 v77, v77, v196
	v_lshlrev_b32_e32 v147, 16, v197
	v_and_b32_e32 v197, 0xffff0000, v197
	v_add_f32_e32 v78, v78, v147
	v_add_f32_e32 v79, v79, v197
	s_waitcnt vmcnt(8)
	v_lshlrev_b32_e32 v147, 16, v198
	v_and_b32_e32 v198, 0xffff0000, v198
	v_add_f32_e32 v72, v72, v147
	v_add_f32_e32 v73, v73, v198
	v_lshlrev_b32_e32 v147, 16, v199
	v_and_b32_e32 v199, 0xffff0000, v199
	v_add_f32_e32 v74, v74, v147
	v_add_f32_e32 v75, v75, v199
	v_lshlrev_b32_e32 v147, 16, v200
	v_and_b32_e32 v200, 0xffff0000, v200
	v_add_f32_e32 v68, v68, v147
	v_add_f32_e32 v69, v69, v200
	v_lshlrev_b32_e32 v147, 16, v201
	v_and_b32_e32 v201, 0xffff0000, v201
	v_add_f32_e32 v70, v70, v147
	v_add_f32_e32 v71, v71, v201
	s_waitcnt vmcnt(7)
	v_lshlrev_b32_e32 v147, 16, v202
	v_and_b32_e32 v202, 0xffff0000, v202
	v_add_f32_e32 v64, v64, v147
	v_add_f32_e32 v65, v65, v202
	v_lshlrev_b32_e32 v147, 16, v203
	v_and_b32_e32 v203, 0xffff0000, v203
	v_add_f32_e32 v66, v66, v147
	v_add_f32_e32 v67, v67, v203
	v_lshlrev_b32_e32 v147, 16, v204
	v_and_b32_e32 v204, 0xffff0000, v204
	v_add_f32_e32 v60, v60, v147
	v_add_f32_e32 v61, v61, v204
	v_lshlrev_b32_e32 v147, 16, v205
	v_and_b32_e32 v205, 0xffff0000, v205
	v_add_f32_e32 v62, v62, v147
	v_add_f32_e32 v63, v63, v205
	s_waitcnt vmcnt(6)
	v_lshlrev_b32_e32 v147, 16, v220
	v_and_b32_e32 v220, 0xffff0000, v220
	v_add_f32_e32 v56, v56, v147
	v_add_f32_e32 v57, v57, v220
	v_lshlrev_b32_e32 v147, 16, v221
	v_and_b32_e32 v221, 0xffff0000, v221
	v_add_f32_e32 v58, v58, v147
	v_add_f32_e32 v59, v59, v221
	v_lshlrev_b32_e32 v147, 16, v222
	v_and_b32_e32 v222, 0xffff0000, v222
	v_add_f32_e32 v52, v52, v147
	v_add_f32_e32 v53, v53, v222
	v_lshlrev_b32_e32 v147, 16, v223
	v_and_b32_e32 v223, 0xffff0000, v223
	v_add_f32_e32 v54, v54, v147
	v_add_f32_e32 v55, v55, v223
	s_waitcnt vmcnt(5)
	v_lshlrev_b32_e32 v147, 16, v224
	v_and_b32_e32 v224, 0xffff0000, v224
	v_add_f32_e32 v48, v48, v147
	v_add_f32_e32 v49, v49, v224
	v_lshlrev_b32_e32 v147, 16, v225
	v_and_b32_e32 v225, 0xffff0000, v225
	v_add_f32_e32 v50, v50, v147
	v_add_f32_e32 v51, v51, v225
	v_lshlrev_b32_e32 v147, 16, v226
	v_and_b32_e32 v226, 0xffff0000, v226
	v_add_f32_e32 v44, v44, v147
	v_add_f32_e32 v45, v45, v226
	v_lshlrev_b32_e32 v147, 16, v227
	v_and_b32_e32 v227, 0xffff0000, v227
	v_add_f32_e32 v46, v46, v147
	v_add_f32_e32 v47, v47, v227
	s_waitcnt vmcnt(4)
	v_lshlrev_b32_e32 v147, 16, v228
	v_and_b32_e32 v228, 0xffff0000, v228
	v_add_f32_e32 v40, v40, v147
	v_add_f32_e32 v41, v41, v228
	v_lshlrev_b32_e32 v147, 16, v229
	v_and_b32_e32 v229, 0xffff0000, v229
	v_add_f32_e32 v42, v42, v147
	v_add_f32_e32 v43, v43, v229
	v_lshlrev_b32_e32 v147, 16, v230
	v_and_b32_e32 v230, 0xffff0000, v230
	v_add_f32_e32 v36, v36, v147
	v_add_f32_e32 v37, v37, v230
	v_lshlrev_b32_e32 v147, 16, v231
	v_and_b32_e32 v231, 0xffff0000, v231
	v_add_f32_e32 v38, v38, v147
	v_add_f32_e32 v39, v39, v231
	s_waitcnt vmcnt(3)
	v_lshlrev_b32_e32 v147, 16, v232
	v_and_b32_e32 v232, 0xffff0000, v232
	v_add_f32_e32 v32, v32, v147
	v_add_f32_e32 v33, v33, v232
	v_lshlrev_b32_e32 v147, 16, v233
	v_and_b32_e32 v233, 0xffff0000, v233
	v_add_f32_e32 v34, v34, v147
	v_add_f32_e32 v35, v35, v233
	v_lshlrev_b32_e32 v147, 16, v234
	v_and_b32_e32 v234, 0xffff0000, v234
	v_add_f32_e32 v28, v28, v147
	v_add_f32_e32 v29, v29, v234
	v_lshlrev_b32_e32 v147, 16, v235
	v_and_b32_e32 v235, 0xffff0000, v235
	v_add_f32_e32 v30, v30, v147
	v_add_f32_e32 v31, v31, v235
	s_waitcnt vmcnt(2)
	v_lshlrev_b32_e32 v147, 16, v158
	v_and_b32_e32 v158, 0xffff0000, v158
	v_add_f32_e32 v24, v24, v147
	v_add_f32_e32 v25, v25, v158
	v_lshlrev_b32_e32 v147, 16, v159
	v_and_b32_e32 v159, 0xffff0000, v159
	v_add_f32_e32 v26, v26, v147
	v_add_f32_e32 v27, v27, v159
	v_lshlrev_b32_e32 v147, 16, v160
	v_and_b32_e32 v160, 0xffff0000, v160
	v_add_f32_e32 v20, v20, v147
	v_add_f32_e32 v21, v21, v160
	v_lshlrev_b32_e32 v147, 16, v161
	v_and_b32_e32 v161, 0xffff0000, v161
	v_add_f32_e32 v22, v22, v147
	v_add_f32_e32 v23, v23, v161
	s_waitcnt vmcnt(1)
	v_lshlrev_b32_e32 v147, 16, v152
	v_and_b32_e32 v152, 0xffff0000, v152
	v_add_f32_e32 v16, v16, v147
	v_add_f32_e32 v17, v17, v152
	v_lshlrev_b32_e32 v147, 16, v153
	v_and_b32_e32 v153, 0xffff0000, v153
	v_add_f32_e32 v18, v18, v147
	v_add_f32_e32 v19, v19, v153
	v_lshlrev_b32_e32 v147, 16, v154
	v_and_b32_e32 v154, 0xffff0000, v154
	v_add_f32_e32 v12, v12, v147
	v_add_f32_e32 v13, v13, v154
	v_lshlrev_b32_e32 v147, 16, v155
	v_and_b32_e32 v155, 0xffff0000, v155
	v_add_f32_e32 v14, v14, v147
	v_add_f32_e32 v15, v15, v155
	s_waitcnt vmcnt(0)
	v_lshlrev_b32_e32 v147, 16, v148
	v_and_b32_e32 v148, 0xffff0000, v148
	v_add_f32_e32 v8, v8, v147
	v_add_f32_e32 v9, v9, v148
	v_lshlrev_b32_e32 v147, 16, v149
	v_and_b32_e32 v149, 0xffff0000, v149
	v_add_f32_e32 v10, v10, v147
	v_add_f32_e32 v11, v11, v149
	v_lshlrev_b32_e32 v147, 16, v150
	v_and_b32_e32 v150, 0xffff0000, v150
	v_add_f32_e32 v4, v4, v147
	v_add_f32_e32 v5, v5, v150
	v_lshlrev_b32_e32 v147, 16, v151
	v_and_b32_e32 v151, 0xffff0000, v151
	v_add_f32_e32 v6, v6, v147
	v_add_f32_e32 v7, v7, v151
	s_mov_b64 s[30:31], s[16:17]
	global_store_dwordx4 v143, v[128:131], s[30:31] offset:0 nt
	global_store_dwordx4 v143, v[124:127], s[30:31] offset:16 nt
	global_store_dwordx4 v143, v[120:123], s[30:31] offset:512 nt
	global_store_dwordx4 v143, v[116:119], s[30:31] offset:528 nt
	s_add_u32 s30, s30, 0x10000
	s_addc_u32 s31, s31, 0
	global_store_dwordx4 v143, v[112:115], s[30:31] offset:0 nt
	global_store_dwordx4 v143, v[108:111], s[30:31] offset:16 nt
	global_store_dwordx4 v143, v[104:107], s[30:31] offset:512 nt
	global_store_dwordx4 v143, v[100:103], s[30:31] offset:528 nt
	s_add_u32 s30, s30, 0x10000
	s_addc_u32 s31, s31, 0
	global_store_dwordx4 v143, v[96:99], s[30:31] offset:0 nt
	global_store_dwordx4 v143, v[92:95], s[30:31] offset:16 nt
	global_store_dwordx4 v143, v[88:91], s[30:31] offset:512 nt
	global_store_dwordx4 v143, v[84:87], s[30:31] offset:528 nt
	s_add_u32 s30, s30, 0x10000
	s_addc_u32 s31, s31, 0
	global_store_dwordx4 v143, v[80:83], s[30:31] offset:0 nt
	global_store_dwordx4 v143, v[76:79], s[30:31] offset:16 nt
	global_store_dwordx4 v143, v[72:75], s[30:31] offset:512 nt
	global_store_dwordx4 v143, v[68:71], s[30:31] offset:528 nt
	s_add_u32 s30, s30, 0x50000
	s_addc_u32 s31, s31, 0
	global_store_dwordx4 v143, v[64:67], s[30:31] offset:0 nt
	global_store_dwordx4 v143, v[60:63], s[30:31] offset:16 nt
	global_store_dwordx4 v143, v[56:59], s[30:31] offset:512 nt
	global_store_dwordx4 v143, v[52:55], s[30:31] offset:528 nt
	s_add_u32 s30, s30, 0x10000
	s_addc_u32 s31, s31, 0
	global_store_dwordx4 v143, v[48:51], s[30:31] offset:0 nt
	global_store_dwordx4 v143, v[44:47], s[30:31] offset:16 nt
	global_store_dwordx4 v143, v[40:43], s[30:31] offset:512 nt
	global_store_dwordx4 v143, v[36:39], s[30:31] offset:528 nt
	s_add_u32 s30, s30, 0x10000
	s_addc_u32 s31, s31, 0
	global_store_dwordx4 v143, v[32:35], s[30:31] offset:0 nt
	global_store_dwordx4 v143, v[28:31], s[30:31] offset:16 nt
	global_store_dwordx4 v143, v[24:27], s[30:31] offset:512 nt
	global_store_dwordx4 v143, v[20:23], s[30:31] offset:528 nt
	s_add_u32 s30, s30, 0x10000
	s_addc_u32 s31, s31, 0
	global_store_dwordx4 v143, v[16:19], s[30:31] offset:0 nt
	global_store_dwordx4 v143, v[12:15], s[30:31] offset:16 nt
	global_store_dwordx4 v143, v[8:11], s[30:31] offset:512 nt
	global_store_dwordx4 v143, v[4:7], s[30:31] offset:528 nt
	s_mov_b64 s[24:25], -1
	s_and_b64 vcc, exec, s[8:9]
	s_cbranch_vccnz .LBB0_811
	s_andn2_b64 vcc, exec, s[18:19]
	s_cbranch_vccnz .LBB0_810
	s_barrier
	s_branch .LBB0_810
